# GEMM tile boundary: next tile's first A-slab DMA issued ahead of the epilogue stores, first K-iteration waits vmcnt(24) instead of draining the 16 stores
# speedup vs baseline: 1.0145x; 1.0016x over previous
; #define PG8_STAGE(bufoff, gbase, voff) do { _Pragma("unroll") for (int _i = 0; _i < 2; ++_i) \
;         __builtin_amdgcn_global_load_lds((const unsigned*)((const char*)(gbase) + (voff)[_i]), (LAS unsigned*)(lds + (bufoff) + ldsw + _i * 8192), 16, 0, 0); } while (0)
; #define PG8_WAIT_V(n) asm volatile("s_waitcnt vmcnt(" #n ")" ::: "memory")
; #define PG8_BAR __builtin_amdgcn_s_barrier()
; template <class Epi, class Sched>
; __device__ __forceinline__ void gemm_phase(LAS unsigned char* lds, const Gemm g, const Sched& S, const Epi& E) {
;     ...
;     for (int i = 0; i < 2; ++i) { int R, C; stage_rc(tid * 16 + i * 8192, R, C); const int Rb = Epi::PERM ? ((R & ~31) + perm32(R & 31)) : R;
;         voffA[i] = (unsigned)(R * K + C) * 2u; voffB[i] = (unsigned)(Rb * K + C) * 2u; }
;     const size_t kstep = (size_t)(BK * 2);
;     const size_t hstep = (size_t)HALF * K * 2;
;     const size_t tstep = 2 * hstep;
;     const unsigned ldsw = (unsigned)wid * 1024u;
;     const int aoff = lds_byte(wr * 64 + fr, fq * 8), boff = lds_byte(wc * 32 + fr, fq * 8);
;     ...
;     Unit cur, nxt; int ui = 0;
;     if (!S.next(0, cur)) return;
;     f32x4 acc[2][2][4][2];
; #pragma unroll
;     for (int a = 0; a < 2; ++a)
; #pragma unroll
;         for (int b = 0; b < 2; ++b)
; #pragma unroll
;             for (int m = 0; m < 4; ++m)
; #pragma unroll
;                 for (int n = 0; n < 2; ++n) acc[a][b][m][n] = (f32x4){0.f, 0.f, 0.f, 0.f};
;     bf16x8 At[4][2], B0[2][2], B1[2][2];
;     const char* cA = (const char*)g.A + (size_t)cur.pm * tstep; const char* cB = (const char*)g.Bt + (size_t)cur.pn * tstep;
;     S.a_ready(cur);
;     PG8_STAGE(PG8_SB(0, 0), cB, voffB); PG8_STAGE(PG8_SA(0, 0), cA, voffA); PG8_STAGE(PG8_SB(0, 1), cB + hstep, voffB); PG8_STAGE(PG8_SA(0, 1), cA + hstep, voffA);
;     if (wr == 1) PG8_BAR;
;     PG8_WAIT_V(4); PG8_BAR;
;     PG8_STAGE(PG8_SB(1, 0), cB + kstep, voffB); PG8_STAGE(PG8_SA(1, 0), cA + kstep, voffA); PG8_STAGE(PG8_SB(1, 1), cB + hstep + kstep, voffB);
;     PG8_WAIT_V(6); PG8_BAR;
.LBB0_183:
	v_mov_b32_e32 v145, v8
	v_lshl_add_u64 v[10:11], s[66:67], 0, v[144:145]
	v_mov_b32_e32 v141, v8
	v_readlane_b32 s70, v241, 22
	s_lshl_b32 s1, s1, 5
	v_lshl_add_u64 v[12:13], s[66:67], 0, v[140:141]
	v_mov_b32_e32 v147, v8
	v_readlane_b32 s71, v241, 23
	s_and_b32 s1, s1, 0x60
	s_add_i32 m0, s9, 0x18000
	v_lshl_add_u64 v[10:11], v[10:11], 0, s[94:95]
	v_lshl_add_u64 v[14:15], s[70:71], 0, v[146:147]
	v_mov_b32_e32 v143, v8
	s_lshl_b32 s2, s0, 13
	s_lshl_b32 s16, s1, 7
	s_waitcnt vmcnt(4)
	s_barrier
	global_load_lds_dwordx4 v[10:11], off
	v_lshl_add_u64 v[10:11], v[12:13], 0, s[94:95]
	s_add_i32 m0, s9, 0x1a000
	s_add_i32 s13, s9, 0x8000
	s_add_i32 s74, s9, 0xa000
	v_lshl_add_u64 v[16:17], s[70:71], 0, v[142:143]
	global_load_lds_dwordx4 v[10:11], off
	v_lshl_add_u64 v[10:11], v[14:15], 0, s[94:95]
	s_mov_b32 m0, s13
	s_add_u32 s14, s66, 0x40080
	global_load_lds_dwordx4 v[10:11], off
	v_lshl_add_u64 v[10:11], v[16:17], 0, s[94:95]
	s_mov_b32 m0, s74
	s_addc_u32 s15, s67, 0
	global_load_lds_dwordx4 v[10:11], off
	s_add_i32 m0, s9, 0x1c000
	v_lshl_add_u64 v[10:11], s[14:15], 0, v[144:145]
	global_load_lds_dwordx4 v[10:11], off
	v_lshl_add_u64 v[10:11], s[14:15], 0, v[140:141]
	s_add_i32 m0, s9, 0x1e000
	v_and_b32_e32 v7, 15, v0
	global_load_lds_dwordx4 v[10:11], off
	v_lshrrev_b32_e32 v10, 1, v0
	v_and_b32_e32 v10, 24, v10
	v_lshlrev_b32_e32 v11, 1, v10
	v_lshlrev_b32_e32 v0, 2, v0
	v_lshl_or_b32 v9, s0, 6, v7
	v_lshl_or_b32 v7, v7, 6, v11
	v_and_b32_e32 v0, 32, v0
	v_bitop3_b32 v11, v7, s2, v0 bitop3:0xde
	v_bitop3_b32 v154, v7, s16, v0 bitop3:0xde
	v_lshlrev_b32_e32 v0, 14, v5
	v_and_b32_e32 v0, 0xffff8000, v0
	v_lshl_add_u32 v0, v4, 11, v0
	v_and_b32_e32 v4, 1, v5
	v_lshl_or_b32 v0, v4, 6, v0
	v_lshl_add_u32 v148, v6, 1, v0
	v_lshlrev_b32_e32 v0, 14, v1
	v_and_b32_e32 v0, 0xffff8000, v0
	s_waitcnt vmcnt(6)
	v_lshl_add_u32 v0, v2, 11, v0
	v_and_b32_e32 v1, 1, v1
	v_lshl_or_b32 v0, v1, 6, v0
	s_lshl_b32 s2, s1, 1
	v_readlane_b32 s0, v241, 20
	v_mov_b32_e32 v149, v8
	v_lshl_add_u32 v150, v3, 1, v0
	v_mov_b32_e32 v151, v8
	s_mov_b32 s14, 0
	v_add_u32_e32 v155, 16, v11
	v_lshlrev_b32_e32 v152, 1, v10
	v_readlane_b32 s15, v241, 17
	s_mov_b32 s75, s0
	s_barrier
	v_readlane_b32 s1, v241, 21
	s_mov_b32 s98, 0

; #define PG8_STAGE(bufoff, gbase, voff) do { _Pragma("unroll") for (int _i = 0; _i < 2; ++_i) \
;         __builtin_amdgcn_global_load_lds((const unsigned*)((const char*)(gbase) + (voff)[_i]), (LAS unsigned*)(lds + (bufoff) + ldsw + _i * 8192), 16, 0, 0); } while (0)
; #define PG8_LDA(dst, b, h) do { _Pragma("unroll") for (int m = 0; m < 4; ++m) _Pragma("unroll") for (int k = 0; k < 2; ++k) dst[m][k] = *(const LAS bf16x8*)(lds + PG8_SA(b, h) + aoff + m * 2048 + k * 1024); } while (0)
; #define PG8_LDB(dst, b, h) do { _Pragma("unroll") for (int n = 0; n < 2; ++n) _Pragma("unroll") for (int k = 0; k < 2; ++k) dst[n][k] = *(const LAS bf16x8*)(lds + PG8_SB(b, h) + boff + n * 2048 + k * 1024); } while (0)
; #define PG8_MMA(ai, bj, At, Bt) do { __builtin_amdgcn_s_setprio(1); _Pragma("unroll") for (int m = 0; m < 4; ++m) _Pragma("unroll") for (int n = 0; n < 2; ++n) _Pragma("unroll") for (int k = 0; k < 2; ++k) \
;         acc[ai][bj][m][n] = __builtin_amdgcn_mfma_f32_16x16x32_bf16(Bt[n][k], At[m][k], acc[ai][bj][m][n], 0, 0, 0); __builtin_amdgcn_s_setprio(0); } while (0)
; #define PG8_WAIT_L(n) asm volatile("s_waitcnt lgkmcnt(" #n ")" ::: "memory")
; #define PG8_BAR __builtin_amdgcn_s_barrier()
; #define PG8_SCHED __builtin_amdgcn_sched_barrier(0)
; template <class Epi, class Sched>
; __device__ __forceinline__ void gemm_phase(LAS unsigned char* lds, const Gemm g, const Sched& S, const Epi& E) {
;     ...
;         for (int t = 0; t < nt; t += 2) {
;             const bool last = (t == nt - 2);
;             const char* a1 = cA + (size_t)(t + 1) * kstep;
;             const char* a2 = last ? nA : cA + (size_t)(t + 2) * kstep; const char* b2 = last ? nB : cB + (size_t)(t + 2) * kstep;
;             const char* a3 = a2 + kstep; const char* b3 = b2 + kstep;
;             if (last && has_next) S.a_ready(nxt);
;             PG8_LDB(B0, 0, 0); PG8_SCHED; PG8_LDA(At, 0, 0); PG8_STAGE(PG8_SA(1, 1), a1 + hstep, voffA);
;             PG8_WAIT_L(8); PG8_BAR; PG8_WAIT_L(0); PG8_MMA(0, 0, At, B0); PG8_BAR; PG8_SCHED;
;             PG8_LDB(B1, 0, 1); PG8_STAGE(PG8_SB(0, 0), b2, voffB);
;             PG8_BAR; PG8_WAIT_L(0); PG8_MMA(0, 1, At, B1); PG8_BAR;
;             PG8_LDA(At, 0, 1); PG8_STAGE(PG8_SA(0, 0), a2, voffA);
;             PG8_BAR; PG8_WAIT_L(0); PG8_MMA(1, 0, At, B0); PG8_BAR; PG8_SCHED;
;             PG8_STAGE(PG8_SB(0, 1), b2 + hstep, voffB);
.LBB0_187:
	s_add_u32 s20, s72, 0xfffc0080
	s_addc_u32 s21, s73, -1
	s_add_i32 s22, 16, 0x10000
	v_add_u32_e32 v153, s22, v154
	ds_read_b128 v[156:159], v153
	ds_read_b128 v[160:163], v153 offset:1024
	ds_read_b128 v[164:167], v153 offset:2048
	ds_read_b128 v[168:171], v153 offset:3072
	s_cmp_eq_u32 s19, 12
	s_cselect_b32 s71, s41, s21
	s_cselect_b32 s70, s78, s20
	s_cselect_b32 s67, s1, s18
	s_cselect_b32 s66, s16, s17
	v_lshl_add_u64 v[216:217], s[72:73], 0, v[148:149]
	s_add_i32 m0, s9, 0xc000
	ds_read_b128 v[172:175], v155
	ds_read_b128 v[188:191], v155 offset:1024
	ds_read_b128 v[192:195], v155 offset:2048
	ds_read_b128 v[196:199], v155 offset:3072
	ds_read_b128 v[200:203], v155 offset:4096
	ds_read_b128 v[204:207], v155 offset:5120
	ds_read_b128 v[208:211], v155 offset:6144
	ds_read_b128 v[212:215], v155 offset:7168
	global_load_lds_dwordx4 v[216:217], off
	v_lshl_add_u64 v[216:217], s[72:73], 0, v[150:151]
	s_add_i32 m0, s9, 0xe000
	s_nop 0
	global_load_lds_dwordx4 v[216:217], off
	s_waitcnt lgkmcnt(8)
	s_barrier
	s_waitcnt lgkmcnt(0)
	s_setprio 1
	s_waitcnt lgkmcnt(0)
	v_mfma_f32_16x16x32_bf16 v[126:129], v[156:159], v[172:175], v[126:129]
	v_mfma_f32_16x16x32_bf16 v[122:125], v[164:167], v[172:175], v[122:125]
	v_mfma_f32_16x16x32_bf16 v[118:121], v[156:159], v[192:195], v[118:121]
	v_mfma_f32_16x16x32_bf16 v[110:113], v[164:167], v[192:195], v[110:113]
	v_mfma_f32_16x16x32_bf16 v[102:105], v[156:159], v[200:203], v[102:105]
	v_mfma_f32_16x16x32_bf16 v[94:97], v[164:167], v[200:203], v[94:97]
	v_mfma_f32_16x16x32_bf16 v[86:89], v[156:159], v[208:211], v[86:89]
	v_mfma_f32_16x16x32_bf16 v[78:81], v[164:167], v[208:211], v[78:81]
	v_mfma_f32_16x16x32_bf16 v[126:129], v[160:163], v[188:191], v[126:129]
	v_mfma_f32_16x16x32_bf16 v[122:125], v[168:171], v[188:191], v[122:125]
	v_mfma_f32_16x16x32_bf16 v[118:121], v[160:163], v[196:199], v[118:121]
	v_mfma_f32_16x16x32_bf16 v[110:113], v[168:171], v[196:199], v[110:113]
	v_mfma_f32_16x16x32_bf16 v[102:105], v[160:163], v[204:207], v[102:105]
	v_mfma_f32_16x16x32_bf16 v[94:97], v[168:171], v[204:207], v[94:97]
	v_mfma_f32_16x16x32_bf16 v[86:89], v[160:163], v[212:215], v[86:89]
	v_mfma_f32_16x16x32_bf16 v[78:81], v[168:171], v[212:215], v[78:81]
	s_setprio 0
	s_barrier
	s_add_i32 s23, 16, 0x14000
	s_add_i32 s20, s22, s8
	v_add_u32_e32 v153, s23, v154
	v_lshl_add_u64 v[232:233], s[66:67], 0, v[144:145]
	s_mov_b32 m0, s20
	ds_read_b128 v[216:219], v153
	ds_read_b128 v[220:223], v153 offset:1024
	ds_read_b128 v[224:227], v153 offset:2048
	ds_read_b128 v[228:231], v153 offset:3072
	global_load_lds_dwordx4 v[232:233], off
	v_lshl_add_u64 v[234:235], s[66:67], 0, v[140:141]
	s_add_i32 m0, s20, 0x2000
	s_nop 0
	global_load_lds_dwordx4 v[234:235], off
	s_barrier
	s_waitcnt lgkmcnt(0)
	s_setprio 1
	s_waitcnt lgkmcnt(0)
	v_mfma_f32_16x16x32_bf16 v[114:117], v[216:219], v[172:175], v[114:117]
	v_mfma_f32_16x16x32_bf16 v[106:109], v[224:227], v[172:175], v[106:109]
	v_mfma_f32_16x16x32_bf16 v[98:101], v[216:219], v[192:195], v[98:101]
	v_mfma_f32_16x16x32_bf16 v[90:93], v[224:227], v[192:195], v[90:93]
	v_mfma_f32_16x16x32_bf16 v[82:85], v[216:219], v[200:203], v[82:85]
	v_mfma_f32_16x16x32_bf16 v[74:77], v[224:227], v[200:203], v[74:77]
	v_mfma_f32_16x16x32_bf16 v[70:73], v[216:219], v[208:211], v[70:73]
	v_mfma_f32_16x16x32_bf16 v[66:69], v[224:227], v[208:211], v[66:69]
	v_mfma_f32_16x16x32_bf16 v[114:117], v[220:223], v[188:191], v[114:117]
	v_mfma_f32_16x16x32_bf16 v[106:109], v[228:231], v[188:191], v[106:109]
	v_mfma_f32_16x16x32_bf16 v[98:101], v[220:223], v[196:199], v[98:101]
	v_mfma_f32_16x16x32_bf16 v[90:93], v[228:231], v[196:199], v[90:93]
	v_mfma_f32_16x16x32_bf16 v[82:85], v[220:223], v[204:207], v[82:85]
	v_mfma_f32_16x16x32_bf16 v[74:77], v[228:231], v[204:207], v[74:77]
	v_mfma_f32_16x16x32_bf16 v[70:73], v[220:223], v[212:215], v[70:73]
	v_mfma_f32_16x16x32_bf16 v[66:69], v[228:231], v[212:215], v[66:69]
	s_setprio 0
	s_mov_b32 m0, s9
	v_lshl_add_u64 v[236:237], s[70:71], 0, v[146:147]
	s_barrier
	ds_read_b128 v[172:175], v155 offset:16384
	ds_read_b128 v[188:191], v155 offset:17408
	ds_read_b128 v[192:195], v155 offset:18432
	ds_read_b128 v[196:199], v155 offset:19456
	ds_read_b128 v[200:203], v155 offset:20480
	ds_read_b128 v[204:207], v155 offset:21504
	ds_read_b128 v[208:211], v155 offset:22528
	ds_read_b128 v[212:215], v155 offset:23552
	global_load_lds_dwordx4 v[236:237], off
	v_lshl_add_u64 v[238:239], s[70:71], 0, v[142:143]
	s_mov_b32 m0, s10
	s_nop 0
	global_load_lds_dwordx4 v[238:239], off
	s_barrier
	s_waitcnt lgkmcnt(0)
	s_setprio 1
	s_waitcnt lgkmcnt(0)
	v_mfma_f32_16x16x32_bf16 v[62:65], v[156:159], v[172:175], v[62:65]
	v_mfma_f32_16x16x32_bf16 v[58:61], v[164:167], v[172:175], v[58:61]
	v_mfma_f32_16x16x32_bf16 v[54:57], v[156:159], v[192:195], v[54:57]
	v_mfma_f32_16x16x32_bf16 v[50:53], v[164:167], v[192:195], v[50:53]
	v_mfma_f32_16x16x32_bf16 v[38:41], v[156:159], v[200:203], v[38:41]
	v_mfma_f32_16x16x32_bf16 v[34:37], v[164:167], v[200:203], v[34:37]
	v_mfma_f32_16x16x32_bf16 v[22:25], v[156:159], v[208:211], v[22:25]
	v_mfma_f32_16x16x32_bf16 v[18:21], v[164:167], v[208:211], v[18:21]
	v_mfma_f32_16x16x32_bf16 v[62:65], v[160:163], v[188:191], v[62:65]
	v_mfma_f32_16x16x32_bf16 v[58:61], v[168:171], v[188:191], v[58:61]
	v_mfma_f32_16x16x32_bf16 v[54:57], v[160:163], v[196:199], v[54:57]
	v_mfma_f32_16x16x32_bf16 v[50:53], v[168:171], v[196:199], v[50:53]
	v_mfma_f32_16x16x32_bf16 v[38:41], v[160:163], v[204:207], v[38:41]
	v_mfma_f32_16x16x32_bf16 v[34:37], v[168:171], v[204:207], v[34:37]
	v_mfma_f32_16x16x32_bf16 v[22:25], v[160:163], v[212:215], v[22:25]
	v_mfma_f32_16x16x32_bf16 v[18:21], v[168:171], v[212:215], v[18:21]
	s_setprio 0
	s_barrier
	s_add_u32 s20, s66, 0x40000
	s_addc_u32 s21, s67, 0
	s_add_i32 s22, s23, s8
	v_lshl_add_u64 v[156:157], s[20:21], 0, v[144:145]
	s_mov_b32 m0, s22
	s_nop 0
	global_load_lds_dwordx4 v[156:157], off
	v_lshl_add_u64 v[156:157], s[20:21], 0, v[140:141]
	s_add_i32 m0, s22, 0x2000
	s_nop 0
	global_load_lds_dwordx4 v[156:157], off
	s_cmp_eq_u32 s98, 0
	s_cbranch_scc1 .Lgdr184_n
	s_waitcnt vmcnt(24)
	s_mov_b32 s98, 0
	s_branch .Lgdr184_j
; #define PG8_STAGE(bufoff, gbase, voff) do { _Pragma("unroll") for (int _i = 0; _i < 2; ++_i) \
;         __builtin_amdgcn_global_load_lds((const unsigned*)((const char*)(gbase) + (voff)[_i]), (LAS unsigned*)(lds + (bufoff) + ldsw + _i * 8192), 16, 0, 0); } while (0)
; #define PG8_LDA(dst, b, h) do { _Pragma("unroll") for (int m = 0; m < 4; ++m) _Pragma("unroll") for (int k = 0; k < 2; ++k) dst[m][k] = *(const LAS bf16x8*)(lds + PG8_SA(b, h) + aoff + m * 2048 + k * 1024); } while (0)
; #define PG8_LDB(dst, b, h) do { _Pragma("unroll") for (int n = 0; n < 2; ++n) _Pragma("unroll") for (int k = 0; k < 2; ++k) dst[n][k] = *(const LAS bf16x8*)(lds + PG8_SB(b, h) + boff + n * 2048 + k * 1024); } while (0)
; #define PG8_MMA(ai, bj, At, Bt) do { __builtin_amdgcn_s_setprio(1); _Pragma("unroll") for (int m = 0; m < 4; ++m) _Pragma("unroll") for (int n = 0; n < 2; ++n) _Pragma("unroll") for (int k = 0; k < 2; ++k) \
;         acc[ai][bj][m][n] = __builtin_amdgcn_mfma_f32_16x16x32_bf16(Bt[n][k], At[m][k], acc[ai][bj][m][n], 0, 0, 0); __builtin_amdgcn_s_setprio(0); } while (0)
; #define PG8_WAIT_V(n) asm volatile("s_waitcnt vmcnt(" #n ")" ::: "memory")
; #define PG8_WAIT_L(n) asm volatile("s_waitcnt lgkmcnt(" #n ")" ::: "memory")
; #define PG8_BAR __builtin_amdgcn_s_barrier()
; #define PG8_SCHED __builtin_amdgcn_sched_barrier(0)
; template <class Epi, class Sched>
; __device__ __forceinline__ void gemm_phase(LAS unsigned char* lds, const Gemm g, const Sched& S, const Epi& E) {
;     ...
;             PG8_WAIT_V(6); PG8_BAR; PG8_MMA(1, 1, At, B1); PG8_BAR;
;             PG8_LDB(B0, 1, 0); PG8_SCHED; PG8_LDA(At, 1, 0); PG8_STAGE(PG8_SA(0, 1), a2 + hstep, voffA);
;             PG8_WAIT_L(8); PG8_BAR; PG8_WAIT_L(0); PG8_MMA(0, 0, At, B0); PG8_BAR; PG8_SCHED;
;             PG8_LDB(B1, 1, 1); PG8_STAGE(PG8_SB(1, 0), b3, voffB);
;             PG8_BAR; PG8_WAIT_L(0); PG8_MMA(0, 1, At, B1); PG8_BAR;
;             PG8_LDA(At, 1, 1); PG8_STAGE(PG8_SA(1, 0), a3, voffA);
;             PG8_BAR; PG8_WAIT_L(0); PG8_MMA(1, 0, At, B0); PG8_BAR; PG8_SCHED;
.Lgdr184_n:
	s_waitcnt vmcnt(6)
.Lgdr184_j:
	s_barrier
	s_setprio 1
	v_mfma_f32_16x16x32_bf16 v[46:49], v[216:219], v[172:175], v[46:49]
	v_mfma_f32_16x16x32_bf16 v[42:45], v[224:227], v[172:175], v[42:45]
	v_mfma_f32_16x16x32_bf16 v[30:33], v[216:219], v[192:195], v[30:33]
	v_mfma_f32_16x16x32_bf16 v[26:29], v[224:227], v[192:195], v[26:29]
	v_mfma_f32_16x16x32_bf16 v[14:17], v[216:219], v[200:203], v[14:17]
	v_mfma_f32_16x16x32_bf16 v[10:13], v[224:227], v[200:203], v[10:13]
	v_mfma_f32_16x16x32_bf16 v[4:7], v[216:219], v[208:211], v[4:7]
	v_mfma_f32_16x16x32_bf16 v[0:3], v[224:227], v[208:211], v[0:3]
	v_mfma_f32_16x16x32_bf16 v[46:49], v[220:223], v[188:191], v[46:49]
	v_mfma_f32_16x16x32_bf16 v[42:45], v[228:231], v[188:191], v[42:45]
	v_mfma_f32_16x16x32_bf16 v[30:33], v[220:223], v[196:199], v[30:33]
	v_mfma_f32_16x16x32_bf16 v[26:29], v[228:231], v[196:199], v[26:29]
	v_mfma_f32_16x16x32_bf16 v[14:17], v[220:223], v[204:207], v[14:17]
	v_mfma_f32_16x16x32_bf16 v[10:13], v[228:231], v[204:207], v[10:13]
	v_mfma_f32_16x16x32_bf16 v[4:7], v[220:223], v[212:215], v[4:7]
	v_mfma_f32_16x16x32_bf16 v[0:3], v[228:231], v[212:215], v[0:3]
	s_setprio 0
	s_add_i32 s22, 16, 0x18000
	v_add_u32_e32 v153, s22, v154
	s_barrier
	ds_read_b128 v[156:159], v153
	ds_read_b128 v[160:163], v153 offset:1024
	ds_read_b128 v[164:167], v153 offset:2048
	ds_read_b128 v[168:171], v153 offset:3072
	s_add_u32 s20, s70, 0x40000
	s_addc_u32 s21, s71, 0
	s_mov_b32 m0, s11
	v_lshl_add_u64 v[216:217], s[20:21], 0, v[146:147]
	ds_read_b128 v[172:175], v155 offset:32768
	ds_read_b128 v[188:191], v155 offset:33792
	ds_read_b128 v[192:195], v155 offset:34816
	ds_read_b128 v[196:199], v155 offset:35840
	ds_read_b128 v[200:203], v155 offset:36864
	ds_read_b128 v[204:207], v155 offset:37888
	ds_read_b128 v[208:211], v155 offset:38912
	ds_read_b128 v[212:215], v155 offset:39936
	global_load_lds_dwordx4 v[216:217], off
	v_lshl_add_u64 v[216:217], s[20:21], 0, v[142:143]
	s_mov_b32 m0, s12
	s_nop 0
	global_load_lds_dwordx4 v[216:217], off
	s_waitcnt lgkmcnt(8)
	s_barrier
	s_waitcnt lgkmcnt(0)
	s_setprio 1
	s_waitcnt lgkmcnt(0)
	v_mfma_f32_16x16x32_bf16 v[126:129], v[156:159], v[172:175], v[126:129]
	v_mfma_f32_16x16x32_bf16 v[122:125], v[164:167], v[172:175], v[122:125]
	v_mfma_f32_16x16x32_bf16 v[118:121], v[156:159], v[192:195], v[118:121]
	v_mfma_f32_16x16x32_bf16 v[110:113], v[164:167], v[192:195], v[110:113]
	v_mfma_f32_16x16x32_bf16 v[102:105], v[156:159], v[200:203], v[102:105]
	v_mfma_f32_16x16x32_bf16 v[94:97], v[164:167], v[200:203], v[94:97]
	v_mfma_f32_16x16x32_bf16 v[86:89], v[156:159], v[208:211], v[86:89]
	v_mfma_f32_16x16x32_bf16 v[78:81], v[164:167], v[208:211], v[78:81]
	v_mfma_f32_16x16x32_bf16 v[126:129], v[160:163], v[188:191], v[126:129]
	v_mfma_f32_16x16x32_bf16 v[122:125], v[168:171], v[188:191], v[122:125]
	v_mfma_f32_16x16x32_bf16 v[118:121], v[160:163], v[196:199], v[118:121]
	v_mfma_f32_16x16x32_bf16 v[110:113], v[168:171], v[196:199], v[110:113]
	v_mfma_f32_16x16x32_bf16 v[102:105], v[160:163], v[204:207], v[102:105]
	v_mfma_f32_16x16x32_bf16 v[94:97], v[168:171], v[204:207], v[94:97]
	v_mfma_f32_16x16x32_bf16 v[86:89], v[160:163], v[212:215], v[86:89]
	v_mfma_f32_16x16x32_bf16 v[78:81], v[168:171], v[212:215], v[78:81]
	s_setprio 0
	s_barrier
	s_add_i32 s23, 16, 0x1c000
	s_add_i32 s20, s22, s8
	v_add_u32_e32 v153, s23, v154
	v_lshl_add_u64 v[232:233], v[232:233], 0, s[94:95]
	s_mov_b32 m0, s20
	ds_read_b128 v[216:219], v153
	ds_read_b128 v[220:223], v153 offset:1024
	ds_read_b128 v[224:227], v153 offset:2048
	ds_read_b128 v[228:231], v153 offset:3072
	global_load_lds_dwordx4 v[232:233], off
	v_lshl_add_u64 v[232:233], v[234:235], 0, s[94:95]
	s_add_i32 m0, s20, 0x2000
	s_nop 0
	global_load_lds_dwordx4 v[232:233], off
	s_barrier
	s_waitcnt lgkmcnt(0)
	s_setprio 1
	s_waitcnt lgkmcnt(0)
	v_mfma_f32_16x16x32_bf16 v[114:117], v[216:219], v[172:175], v[114:117]
	v_mfma_f32_16x16x32_bf16 v[106:109], v[224:227], v[172:175], v[106:109]
	v_mfma_f32_16x16x32_bf16 v[98:101], v[216:219], v[192:195], v[98:101]
	v_mfma_f32_16x16x32_bf16 v[90:93], v[224:227], v[192:195], v[90:93]
	v_mfma_f32_16x16x32_bf16 v[82:85], v[216:219], v[200:203], v[82:85]
	v_mfma_f32_16x16x32_bf16 v[74:77], v[224:227], v[200:203], v[74:77]
	v_mfma_f32_16x16x32_bf16 v[70:73], v[216:219], v[208:211], v[70:73]
	v_mfma_f32_16x16x32_bf16 v[66:69], v[224:227], v[208:211], v[66:69]
	v_mfma_f32_16x16x32_bf16 v[114:117], v[220:223], v[188:191], v[114:117]
	v_mfma_f32_16x16x32_bf16 v[106:109], v[228:231], v[188:191], v[106:109]
	v_mfma_f32_16x16x32_bf16 v[98:101], v[220:223], v[196:199], v[98:101]
	v_mfma_f32_16x16x32_bf16 v[90:93], v[228:231], v[196:199], v[90:93]
	v_mfma_f32_16x16x32_bf16 v[82:85], v[220:223], v[204:207], v[82:85]
	v_mfma_f32_16x16x32_bf16 v[74:77], v[228:231], v[204:207], v[74:77]
	v_mfma_f32_16x16x32_bf16 v[70:73], v[220:223], v[212:215], v[70:73]
	v_mfma_f32_16x16x32_bf16 v[66:69], v[228:231], v[212:215], v[66:69]
	s_setprio 0
	s_mov_b32 m0, s13
	v_lshl_add_u64 v[232:233], v[236:237], 0, s[94:95]
	s_barrier
	ds_read_b128 v[172:175], v155 offset:49152
	ds_read_b128 v[188:191], v155 offset:50176
	ds_read_b128 v[192:195], v155 offset:51200
	ds_read_b128 v[196:199], v155 offset:52224
	ds_read_b128 v[200:203], v155 offset:53248
	ds_read_b128 v[204:207], v155 offset:54272
	ds_read_b128 v[208:211], v155 offset:55296
	ds_read_b128 v[212:215], v155 offset:56320
	global_load_lds_dwordx4 v[232:233], off
	v_lshl_add_u64 v[232:233], v[238:239], 0, s[94:95]
	s_mov_b32 m0, s74
	s_nop 0
	global_load_lds_dwordx4 v[232:233], off
	s_barrier
; #define PG8_STAGE(bufoff, gbase, voff) do { _Pragma("unroll") for (int _i = 0; _i < 2; ++_i) \
;         __builtin_amdgcn_global_load_lds((const unsigned*)((const char*)(gbase) + (voff)[_i]), (LAS unsigned*)(lds + (bufoff) + ldsw + _i * 8192), 16, 0, 0); } while (0)
; #define PG8_MMA(ai, bj, At, Bt) do { __builtin_amdgcn_s_setprio(1); _Pragma("unroll") for (int m = 0; m < 4; ++m) _Pragma("unroll") for (int n = 0; n < 2; ++n) _Pragma("unroll") for (int k = 0; k < 2; ++k) \
;         acc[ai][bj][m][n] = __builtin_amdgcn_mfma_f32_16x16x32_bf16(Bt[n][k], At[m][k], acc[ai][bj][m][n], 0, 0, 0); __builtin_amdgcn_s_setprio(0); } while (0)
; #define PG8_WAIT_V(n) asm volatile("s_waitcnt vmcnt(" #n ")" ::: "memory")
; #define PG8_WAIT_L(n) asm volatile("s_waitcnt lgkmcnt(" #n ")" ::: "memory")
; #define PG8_BAR __builtin_amdgcn_s_barrier()
; #define PG8_SCHED __builtin_amdgcn_sched_barrier(0)
; template <class Epi, class Sched>
; __device__ __forceinline__ void gemm_phase(LAS unsigned char* lds, const Gemm g, const Sched& S, const Epi& E) {
;     ...
;             PG8_BAR; PG8_WAIT_L(0); PG8_MMA(1, 0, At, B0); PG8_BAR; PG8_SCHED;
;             PG8_STAGE(PG8_SB(1, 1), b3 + hstep, voffB);
;             PG8_WAIT_V(6); PG8_BAR; PG8_MMA(1, 1, At, B1); PG8_BAR;
;         }
	s_waitcnt lgkmcnt(0)
	s_setprio 1
	s_waitcnt lgkmcnt(0)
	v_mfma_f32_16x16x32_bf16 v[62:65], v[156:159], v[172:175], v[62:65]
	v_mfma_f32_16x16x32_bf16 v[58:61], v[164:167], v[172:175], v[58:61]
	v_mfma_f32_16x16x32_bf16 v[54:57], v[156:159], v[192:195], v[54:57]
	v_mfma_f32_16x16x32_bf16 v[50:53], v[164:167], v[192:195], v[50:53]
	v_mfma_f32_16x16x32_bf16 v[38:41], v[156:159], v[200:203], v[38:41]
	v_mfma_f32_16x16x32_bf16 v[34:37], v[164:167], v[200:203], v[34:37]
	v_mfma_f32_16x16x32_bf16 v[22:25], v[156:159], v[208:211], v[22:25]
	v_mfma_f32_16x16x32_bf16 v[18:21], v[164:167], v[208:211], v[18:21]
	v_mfma_f32_16x16x32_bf16 v[62:65], v[160:163], v[188:191], v[62:65]
	v_mfma_f32_16x16x32_bf16 v[58:61], v[168:171], v[188:191], v[58:61]
	v_mfma_f32_16x16x32_bf16 v[54:57], v[160:163], v[196:199], v[54:57]
	v_mfma_f32_16x16x32_bf16 v[50:53], v[168:171], v[196:199], v[50:53]
	v_mfma_f32_16x16x32_bf16 v[38:41], v[160:163], v[204:207], v[38:41]
	v_mfma_f32_16x16x32_bf16 v[34:37], v[168:171], v[204:207], v[34:37]
	v_mfma_f32_16x16x32_bf16 v[22:25], v[160:163], v[212:215], v[22:25]
	v_mfma_f32_16x16x32_bf16 v[18:21], v[168:171], v[212:215], v[18:21]
	s_setprio 0
	s_barrier
	s_add_u32 s20, s66, 0x40080
	s_addc_u32 s21, s67, 0
	s_add_i32 s22, s23, s8
	v_lshl_add_u64 v[156:157], s[20:21], 0, v[144:145]
	s_mov_b32 m0, s22
	s_nop 0
	global_load_lds_dwordx4 v[156:157], off
	v_lshl_add_u64 v[156:157], s[20:21], 0, v[140:141]
	s_add_i32 m0, s22, 0x2000
	s_nop 0
	global_load_lds_dwordx4 v[156:157], off
	s_waitcnt vmcnt(6)
	s_barrier
	s_setprio 1
	v_mfma_f32_16x16x32_bf16 v[46:49], v[216:219], v[172:175], v[46:49]
	v_mfma_f32_16x16x32_bf16 v[42:45], v[224:227], v[172:175], v[42:45]
	v_mfma_f32_16x16x32_bf16 v[30:33], v[216:219], v[192:195], v[30:33]
	v_mfma_f32_16x16x32_bf16 v[26:29], v[224:227], v[192:195], v[26:29]
	v_mfma_f32_16x16x32_bf16 v[14:17], v[216:219], v[200:203], v[14:17]
	v_mfma_f32_16x16x32_bf16 v[10:13], v[224:227], v[200:203], v[10:13]
	v_mfma_f32_16x16x32_bf16 v[4:7], v[216:219], v[208:211], v[4:7]
	v_mfma_f32_16x16x32_bf16 v[0:3], v[224:227], v[208:211], v[0:3]
	v_mfma_f32_16x16x32_bf16 v[46:49], v[220:223], v[188:191], v[46:49]
	v_mfma_f32_16x16x32_bf16 v[42:45], v[228:231], v[188:191], v[42:45]
	v_mfma_f32_16x16x32_bf16 v[30:33], v[220:223], v[196:199], v[30:33]
	v_mfma_f32_16x16x32_bf16 v[26:29], v[228:231], v[196:199], v[26:29]
	v_mfma_f32_16x16x32_bf16 v[14:17], v[220:223], v[204:207], v[14:17]
	v_mfma_f32_16x16x32_bf16 v[10:13], v[228:231], v[204:207], v[10:13]
	v_mfma_f32_16x16x32_bf16 v[4:7], v[220:223], v[212:215], v[4:7]
	v_mfma_f32_16x16x32_bf16 v[0:3], v[228:231], v[212:215], v[0:3]
	s_setprio 0
	s_add_i32 s19, s19, 2
	s_add_u32 s72, s72, 0x100
	s_addc_u32 s73, s73, 0
	s_add_u32 s17, s17, 0x100
	s_addc_u32 s18, s18, 0
	s_cmp_gt_u32 s19, 13
	s_barrier
	s_cbranch_scc0 .LBB0_187
	s_cmp_lg_u64 s[38:39], 0
	s_cbranch_scc1 .Lgdr184_e
	s_add_u32 s100, s42, 0x40080
	s_addc_u32 s101, s43, 0
	v_lshl_add_u64 v[216:217], s[100:101], 0, v[148:149]
	s_add_i32 m0, s9, 0xc000
	s_nop 0
	global_load_lds_dwordx4 v[216:217], off
	v_lshl_add_u64 v[216:217], s[100:101], 0, v[150:151]
	s_add_i32 m0, s9, 0xe000
	s_nop 0
	global_load_lds_dwordx4 v[216:217], off
	s_mov_b32 s98, 1
; __device__ __forceinline__ unsigned pk_bf16(float a, float b) { f32x2 v = {a, b}; bf2_t r = __builtin_convertvector(v, bf2_t); return __builtin_bit_cast(unsigned, r); }
; #define PG8_WAIT_V(n) asm volatile("s_waitcnt vmcnt(" #n ")" ::: "memory")
; #define PG8_BAR __builtin_amdgcn_s_barrier()
;     __device__ __forceinline__ void operator()(const f32x4 (&acc)[2][2][4][2], const Unit& u, int wr, int wc, int fr, int fq) const {
;         const int row0 = u.pm * BM + wr * 64 + fr; int colt = u.pn * BM; bf16_t* base = O;
;         if (split_cols) { const int t = colt / split_cols; base += (size_t)t * split_stride; colt -= t * split_cols; }
;         const int col0 = colt + wc * 32 + 8 * fq;
; #pragma unroll
;         for (int ai = 0; ai < 2; ++ai)
; #pragma unroll
;             for (int m = 0; m < 4; ++m) { const int row = row0 + ai * HALF + m * 16;
;                 bf16_t* rowp = slot_stride ? base + (size_t)(colt >> 7) * slot_stride + (size_t)row * 128 + wc * 32 + 8 * fq : base + (size_t)row * ldc + col0;
; #pragma unroll
;                 for (int bj = 0; bj < 2; ++bj) { const f32x4 v0 = acc[ai][bj][m][0], v1 = acc[ai][bj][m][1];
;                     u32x4 w; w.x = pk_bf16(v0[0], v0[1]); w.y = pk_bf16(v0[2], v0[3]); w.z = pk_bf16(v1[0], v1[1]); w.w = pk_bf16(v1[2], v1[3]);
;                     *(u32x4*)(rowp + (slot_stride ? (size_t)bj * slot_stride : (size_t)bj * HALF)) = w; } }
; template <class Epi, class Sched>
; __device__ __forceinline__ void gemm_phase(LAS unsigned char* lds, const Gemm g, const Sched& S, const Epi& E) {
;     ...
;         E(acc, cur, wr, wc, fr, fq); S.done(cur);
;         if (!has_next) break;
; #pragma unroll
;         for (int a = 0; a < 2; ++a)
; #pragma unroll
;             for (int b = 0; b < 2; ++b)
; #pragma unroll
;                 for (int m = 0; m < 4; ++m)
; #pragma unroll
;                     for (int n = 0; n < 2; ++n) acc[a][b][m][n] = (f32x4){0.f, 0.f, 0.f, 0.f};
;         cur = nxt; cA = nA; cB = nB; ++ui;
;     }
;     PG8_WAIT_V(0);
;     if (wr == 0) PG8_BAR;
;     PG8_BAR;
.Lgdr184_e:
	v_lshl_add_u32 v156, s75, 8, v9
	s_lshl_b32 s1, s15, 1
	s_mul_i32 s15, s15, 0x1100000
	s_mul_hi_i32 s1, s1, 0x880000
	s_add_u32 s66, s82, s15
	v_ashrrev_i32_e32 v157, 31, v156
	s_addc_u32 s67, s83, s1
	v_lshlrev_b64 v[158:159], 8, v[156:157]
	v_lshl_add_u64 v[158:159], s[66:67], 0, v[158:159]
	v_lshl_add_u64 v[158:159], v[158:159], 0, s[2:3]
	v_mov_b32_e32 v153, v8
	v_lshl_add_u64 v[158:159], v[158:159], 0, v[152:153]
	v_cvt_pk_bf16_f32 v114, v114, v115
	v_cvt_pk_bf16_f32 v115, v116, v117
	v_cvt_pk_bf16_f32 v116, v106, v107
	v_add_co_u32_e32 v106, vcc, s87, v158
	v_cvt_pk_bf16_f32 v117, v108, v109
	s_nop 0
	v_addc_co_u32_e32 v107, vcc, 0, v159, vcc
	global_store_dwordx4 v[106:107], v[114:117], off
	v_or_b32_e32 v106, 16, v156
	v_ashrrev_i32_e32 v107, 31, v106
	v_lshlrev_b64 v[106:107], 8, v[106:107]
	v_lshl_add_u64 v[106:107], s[66:67], 0, v[106:107]
	v_lshl_add_u64 v[106:107], v[106:107], 0, s[2:3]
	v_lshl_add_u64 v[114:115], v[106:107], 0, v[152:153]
	v_cvt_pk_bf16_f32 v98, v98, v99
	v_cvt_pk_bf16_f32 v99, v100, v101
	v_cvt_pk_bf16_f32 v100, v90, v91
	v_add_co_u32_e32 v90, vcc, s87, v114
	v_cvt_pk_bf16_f32 v101, v92, v93
	s_nop 0
	v_addc_co_u32_e32 v91, vcc, 0, v115, vcc
	global_store_dwordx4 v[90:91], v[98:101], off
	v_or_b32_e32 v90, 32, v156
	v_ashrrev_i32_e32 v91, 31, v90
	v_lshlrev_b64 v[90:91], 8, v[90:91]
	v_lshl_add_u64 v[90:91], s[66:67], 0, v[90:91]
	v_lshl_add_u64 v[90:91], v[90:91], 0, s[2:3]
	v_lshl_add_u64 v[98:99], v[90:91], 0, v[152:153]
	v_cvt_pk_bf16_f32 v82, v82, v83
	v_cvt_pk_bf16_f32 v83, v84, v85
	v_cvt_pk_bf16_f32 v84, v74, v75
	v_add_co_u32_e32 v74, vcc, s87, v98
	v_cvt_pk_bf16_f32 v85, v76, v77
	s_nop 0
	v_addc_co_u32_e32 v75, vcc, 0, v99, vcc
	global_store_dwordx4 v[74:75], v[82:85], off
	v_or_b32_e32 v74, 48, v156
	v_ashrrev_i32_e32 v75, 31, v74
	v_lshlrev_b64 v[74:75], 8, v[74:75]
	v_lshl_add_u64 v[74:75], s[66:67], 0, v[74:75]
	v_lshl_add_u64 v[74:75], v[74:75], 0, s[2:3]
	v_lshl_add_u64 v[82:83], v[74:75], 0, v[152:153]
	v_cvt_pk_bf16_f32 v70, v70, v71
	v_cvt_pk_bf16_f32 v71, v72, v73
	v_cvt_pk_bf16_f32 v72, v66, v67
	v_add_co_u32_e32 v66, vcc, s87, v82
	s_mov_b32 s1, 0x9000
	s_nop 0
	v_addc_co_u32_e32 v67, vcc, 0, v83, vcc
	v_cvt_pk_bf16_f32 v62, v62, v63
	v_cvt_pk_bf16_f32 v63, v64, v65
	v_cvt_pk_bf16_f32 v64, v58, v59
	v_add_co_u32_e32 v58, vcc, s1, v158
	s_mov_b32 s1, 0x889000
	s_nop 0
	v_addc_co_u32_e32 v59, vcc, 0, v159, vcc
	v_cvt_pk_bf16_f32 v65, v60, v61
	v_add_co_u32_e32 v60, vcc, s1, v158
	v_cvt_pk_bf16_f32 v30, v30, v31
	s_nop 0
	v_addc_co_u32_e32 v61, vcc, 0, v159, vcc
	v_cvt_pk_bf16_f32 v31, v32, v33
	v_cvt_pk_bf16_f32 v32, v26, v27
	v_cvt_pk_bf16_f32 v33, v28, v29
	s_mov_b32 s1, 0xb000
	global_store_dwordx4 v[60:61], v[30:33], off
	v_cvt_pk_bf16_f32 v14, v14, v15
	v_cvt_pk_bf16_f32 v15, v16, v17
	v_add_co_u32_e32 v30, vcc, s1, v158
	s_mov_b32 s1, 0x88a000
	s_nop 0
	v_addc_co_u32_e32 v31, vcc, 0, v159, vcc
	v_cvt_pk_bf16_f32 v16, v10, v11
	v_add_co_u32_e32 v10, vcc, s1, v158
	v_cvt_pk_bf16_f32 v4, v4, v5
	s_nop 0
	v_addc_co_u32_e32 v11, vcc, 0, v159, vcc
	v_cvt_pk_bf16_f32 v5, v6, v7
	v_cvt_pk_bf16_f32 v6, v0, v1
	v_add_co_u32_e32 v0, vcc, 0x88b000, v158
	v_cvt_pk_bf16_f32 v17, v12, v13
	s_nop 0
	v_addc_co_u32_e32 v1, vcc, 0, v159, vcc
	v_cvt_pk_bf16_f32 v126, v126, v127
	v_cvt_pk_bf16_f32 v127, v128, v129
	v_cvt_pk_bf16_f32 v128, v122, v123
	v_cvt_pk_bf16_f32 v129, v124, v125
	v_cvt_pk_bf16_f32 v106, v118, v119
	v_cvt_pk_bf16_f32 v107, v120, v121
	v_cvt_pk_bf16_f32 v108, v110, v111
	v_cvt_pk_bf16_f32 v109, v112, v113
	v_cvt_pk_bf16_f32 v90, v102, v103
	v_cvt_pk_bf16_f32 v91, v104, v105
	v_cvt_pk_bf16_f32 v92, v94, v95
	v_cvt_pk_bf16_f32 v93, v96, v97
	v_cvt_pk_bf16_f32 v74, v86, v87
	v_cvt_pk_bf16_f32 v75, v88, v89
	v_cvt_pk_bf16_f32 v76, v78, v79
	v_cvt_pk_bf16_f32 v77, v80, v81
	v_cvt_pk_bf16_f32 v73, v68, v69
	v_cvt_pk_bf16_f32 v46, v46, v47
	v_cvt_pk_bf16_f32 v47, v48, v49
	v_cvt_pk_bf16_f32 v48, v42, v43
	v_cvt_pk_bf16_f32 v49, v44, v45
	v_cvt_pk_bf16_f32 v42, v54, v55
	v_cvt_pk_bf16_f32 v43, v56, v57
	v_cvt_pk_bf16_f32 v44, v50, v51
	v_cvt_pk_bf16_f32 v45, v52, v53
	v_cvt_pk_bf16_f32 v26, v38, v39
	v_cvt_pk_bf16_f32 v27, v40, v41
	v_cvt_pk_bf16_f32 v28, v34, v35
	v_cvt_pk_bf16_f32 v29, v36, v37
	global_store_dwordx4 v[10:11], v[14:17], off
	v_cvt_pk_bf16_f32 v10, v22, v23
	v_cvt_pk_bf16_f32 v11, v24, v25
	v_cvt_pk_bf16_f32 v12, v18, v19
	v_cvt_pk_bf16_f32 v13, v20, v21
	v_cvt_pk_bf16_f32 v7, v2, v3
	s_and_b64 vcc, exec, s[38:39]
	s_mov_b32 s15, s0
	s_mov_b32 s75, s40
	s_mov_b64 s[66:67], s[88:89]
	s_mov_b64 s[70:71], s[42:43]
	global_store_dwordx4 v[158:159], v[126:129], off
	global_store_dwordx4 v[114:115], v[106:109], off
	global_store_dwordx4 v[98:99], v[90:93], off
	global_store_dwordx4 v[82:83], v[74:77], off
	global_store_dwordx4 v[66:67], v[70:73], off
	global_store_dwordx4 v[58:59], v[62:65], off offset:-4096
	global_store_dwordx4 v[60:61], v[46:49], off offset:-4096
	global_store_dwordx4 v[58:59], v[42:45], off
	global_store_dwordx4 v[30:31], v[26:29], off offset:-4096
	global_store_dwordx4 v[30:31], v[10:13], off
	global_store_dwordx4 v[0:1], v[4:7], off
	s_cbranch_vccz .LBB0_184
	s_waitcnt vmcnt(0)
	v_readlane_b32 s14, v244, 49
	v_readlane_b32 s16, v244, 51
	v_readlane_b32 s70, v244, 55
	s_cmpk_gt_u32 s5, 0xff
	v_readlane_b32 s15, v244, 50
	v_readlane_b32 s17, v244, 52
	v_readlane_b32 s71, v244, 56
	s_cbranch_scc1 .LBB0_191
	s_barrier

; #define PG8_STAGE(bufoff, gbase, voff) do { _Pragma("unroll") for (int _i = 0; _i < 2; ++_i) \
;         __builtin_amdgcn_global_load_lds((const unsigned*)((const char*)(gbase) + (voff)[_i]), (LAS unsigned*)(lds + (bufoff) + ldsw + _i * 8192), 16, 0, 0); } while (0)
; #define PG8_WAIT_V(n) asm volatile("s_waitcnt vmcnt(" #n ")" ::: "memory")
; #define PG8_BAR __builtin_amdgcn_s_barrier()
; template <class Epi, class Sched>
; __device__ __forceinline__ void gemm_phase(LAS unsigned char* lds, const Gemm g, const Sched& S, const Epi& E) {
;     ...
;     for (int i = 0; i < 2; ++i) { int R, C; stage_rc(tid * 16 + i * 8192, R, C); const int Rb = Epi::PERM ? ((R & ~31) + perm32(R & 31)) : R;
;         voffA[i] = (unsigned)(R * K + C) * 2u; voffB[i] = (unsigned)(Rb * K + C) * 2u; }
;     const size_t kstep = (size_t)(BK * 2);
;     const size_t hstep = (size_t)HALF * K * 2;
;     const size_t tstep = 2 * hstep;
;     const unsigned ldsw = (unsigned)wid * 1024u;
;     const int aoff = lds_byte(wr * 64 + fr, fq * 8), boff = lds_byte(wc * 32 + fr, fq * 8);
;     ...
;     Unit cur, nxt; int ui = 0;
;     if (!S.next(0, cur)) return;
;     f32x4 acc[2][2][4][2];
; #pragma unroll
;     for (int a = 0; a < 2; ++a)
; #pragma unroll
;         for (int b = 0; b < 2; ++b)
; #pragma unroll
;             for (int m = 0; m < 4; ++m)
; #pragma unroll
;                 for (int n = 0; n < 2; ++n) acc[a][b][m][n] = (f32x4){0.f, 0.f, 0.f, 0.f};
;     bf16x8 At[4][2], B0[2][2], B1[2][2];
;     const char* cA = (const char*)g.A + (size_t)cur.pm * tstep; const char* cB = (const char*)g.Bt + (size_t)cur.pn * tstep;
;     S.a_ready(cur);
;     PG8_STAGE(PG8_SB(0, 0), cB, voffB); PG8_STAGE(PG8_SA(0, 0), cA, voffA); PG8_STAGE(PG8_SB(0, 1), cB + hstep, voffB); PG8_STAGE(PG8_SA(0, 1), cA + hstep, voffA);
;     if (wr == 1) PG8_BAR;
;     PG8_WAIT_V(4); PG8_BAR;
;     PG8_STAGE(PG8_SB(1, 0), cB + kstep, voffB); PG8_STAGE(PG8_SA(1, 0), cA + kstep, voffA); PG8_STAGE(PG8_SB(1, 1), cB + hstep + kstep, voffB);
;     PG8_WAIT_V(6); PG8_BAR;
.LBB0_511:
	v_lshrrev_b32_e32 v18, 1, v6
	v_and_b32_e32 v18, 24, v18
	s_lshl_b32 s13, s13, 5
	v_mov_b32_e32 v145, v8
	v_and_b32_e32 v7, 15, v6
	v_lshlrev_b32_e32 v19, 1, v18
	v_lshlrev_b32_e32 v6, 2, v6
	s_and_b32 s15, s13, 0x60
	v_lshl_add_u64 v[10:11], s[74:75], 0, v[144:145]
	v_mov_b32_e32 v141, v8
	v_lshl_or_b32 v9, s14, 6, v7
	v_lshl_or_b32 v7, v7, 6, v19
	s_lshl_b32 s14, s14, 13
	v_and_b32_e32 v6, 32, v6
	s_lshl_b32 s13, s15, 7
	v_lshl_add_u64 v[12:13], s[74:75], 0, v[140:141]
	v_mov_b32_e32 v147, v8
	v_bitop3_b32 v19, v7, s14, v6 bitop3:0xde
	v_bitop3_b32 v152, v7, s13, v6 bitop3:0xde
	s_add_i32 m0, s1, 0x18000
	v_lshl_add_u64 v[6:7], v[10:11], 0, s[94:95]
	v_lshl_add_u64 v[14:15], s[72:73], 0, v[146:147]
	v_mov_b32_e32 v143, v8
	s_waitcnt vmcnt(4)
	s_barrier
	global_load_lds_dwordx4 v[6:7], off
	v_lshl_add_u64 v[6:7], v[12:13], 0, s[94:95]
	s_add_i32 m0, s1, 0x1a000
	s_add_i32 s13, s1, 0x8000
	s_add_i32 s14, s1, 0xa000
	v_lshl_add_u64 v[16:17], s[72:73], 0, v[142:143]
	global_load_lds_dwordx4 v[6:7], off
	v_lshl_add_u64 v[6:7], v[14:15], 0, s[94:95]
	s_mov_b32 m0, s13
	s_add_u32 s16, s74, 0x40080
	global_load_lds_dwordx4 v[6:7], off
	v_lshl_add_u64 v[6:7], v[16:17], 0, s[94:95]
	s_mov_b32 m0, s14
	s_addc_u32 s17, s75, 0
	global_load_lds_dwordx4 v[6:7], off
	s_add_i32 m0, s1, 0x1c000
	v_lshl_add_u64 v[6:7], s[16:17], 0, v[144:145]
	global_load_lds_dwordx4 v[6:7], off
	v_lshl_add_u64 v[6:7], s[16:17], 0, v[140:141]
	s_add_i32 m0, s1, 0x1e000
	v_or_b32_e32 v153, s15, v18
	global_load_lds_dwordx4 v[6:7], off
	v_lshlrev_b32_e32 v6, 14, v4
	v_and_b32_e32 v6, 0xffff8000, v6
	v_lshl_add_u32 v3, v3, 11, v6
	v_and_b32_e32 v4, 1, v4
	v_lshl_or_b32 v3, v4, 6, v3
	v_lshl_add_u32 v148, v5, 1, v3
	v_lshlrev_b32_e32 v3, 14, v0
	v_and_b32_e32 v3, 0xffff8000, v3
	s_waitcnt vmcnt(6)
	v_lshl_add_u32 v1, v1, 11, v3
	v_and_b32_e32 v0, 1, v0
	v_lshl_or_b32 v0, v0, 6, v1
	v_mov_b32_e32 v149, v8
	v_lshl_add_u32 v150, v2, 1, v0
	v_mov_b32_e32 v151, v8
	s_mov_b32 s15, 0
	v_add_u32_e32 v154, 16, v19
	s_barrier
	s_mov_b32 s98, 0

; #define PG8_STAGE(bufoff, gbase, voff) do { _Pragma("unroll") for (int _i = 0; _i < 2; ++_i) \
;         __builtin_amdgcn_global_load_lds((const unsigned*)((const char*)(gbase) + (voff)[_i]), (LAS unsigned*)(lds + (bufoff) + ldsw + _i * 8192), 16, 0, 0); } while (0)
; #define PG8_LDA(dst, b, h) do { _Pragma("unroll") for (int m = 0; m < 4; ++m) _Pragma("unroll") for (int k = 0; k < 2; ++k) dst[m][k] = *(const LAS bf16x8*)(lds + PG8_SA(b, h) + aoff + m * 2048 + k * 1024); } while (0)
; #define PG8_LDB(dst, b, h) do { _Pragma("unroll") for (int n = 0; n < 2; ++n) _Pragma("unroll") for (int k = 0; k < 2; ++k) dst[n][k] = *(const LAS bf16x8*)(lds + PG8_SB(b, h) + boff + n * 2048 + k * 1024); } while (0)
; #define PG8_MMA(ai, bj, At, Bt) do { __builtin_amdgcn_s_setprio(1); _Pragma("unroll") for (int m = 0; m < 4; ++m) _Pragma("unroll") for (int n = 0; n < 2; ++n) _Pragma("unroll") for (int k = 0; k < 2; ++k) \
;         acc[ai][bj][m][n] = __builtin_amdgcn_mfma_f32_16x16x32_bf16(Bt[n][k], At[m][k], acc[ai][bj][m][n], 0, 0, 0); __builtin_amdgcn_s_setprio(0); } while (0)
; #define PG8_WAIT_L(n) asm volatile("s_waitcnt lgkmcnt(" #n ")" ::: "memory")
; #define PG8_BAR __builtin_amdgcn_s_barrier()
; #define PG8_SCHED __builtin_amdgcn_sched_barrier(0)
; template <class Epi, class Sched>
; __device__ __forceinline__ void gemm_phase(LAS unsigned char* lds, const Gemm g, const Sched& S, const Epi& E) {
;     ...
;         for (int t = 0; t < nt; t += 2) {
;             const bool last = (t == nt - 2);
;             const char* a1 = cA + (size_t)(t + 1) * kstep;
;             const char* a2 = last ? nA : cA + (size_t)(t + 2) * kstep; const char* b2 = last ? nB : cB + (size_t)(t + 2) * kstep;
;             const char* a3 = a2 + kstep; const char* b3 = b2 + kstep;
;             if (last && has_next) S.a_ready(nxt);
;             PG8_LDB(B0, 0, 0); PG8_SCHED; PG8_LDA(At, 0, 0); PG8_STAGE(PG8_SA(1, 1), a1 + hstep, voffA);
;             PG8_WAIT_L(8); PG8_BAR; PG8_WAIT_L(0); PG8_MMA(0, 0, At, B0); PG8_BAR; PG8_SCHED;
;             PG8_LDB(B1, 0, 1); PG8_STAGE(PG8_SB(0, 0), b2, voffB);
;             PG8_BAR; PG8_WAIT_L(0); PG8_MMA(0, 1, At, B1); PG8_BAR;
;             PG8_LDA(At, 0, 1); PG8_STAGE(PG8_SA(0, 0), a2, voffA);
;             PG8_BAR; PG8_WAIT_L(0); PG8_MMA(1, 0, At, B0); PG8_BAR; PG8_SCHED;
;             PG8_STAGE(PG8_SB(0, 1), b2 + hstep, voffB);
.LBB0_515:
	s_add_u32 s20, vcc_lo, 0xfffc0080
	s_addc_u32 s21, vcc_hi, -1
	s_add_i32 s22, 16, 0x10000
	v_add_u32_e32 v155, s22, v152
	ds_read_b128 v[156:159], v155
	ds_read_b128 v[160:163], v155 offset:1024
	ds_read_b128 v[164:167], v155 offset:2048
	ds_read_b128 v[168:171], v155 offset:3072
	s_cmp_eq_u32 s19, 12
	s_cselect_b32 s73, s89, s21
	s_cselect_b32 s72, s16, s20
	s_cselect_b32 s67, s17, s18
	s_cselect_b32 s66, s43, s74
	v_lshl_add_u64 v[216:217], vcc, 0, v[148:149]
	s_add_i32 m0, s1, 0xc000
	ds_read_b128 v[172:175], v154
	ds_read_b128 v[188:191], v154 offset:1024
	ds_read_b128 v[192:195], v154 offset:2048
	ds_read_b128 v[196:199], v154 offset:3072
	ds_read_b128 v[200:203], v154 offset:4096
	ds_read_b128 v[204:207], v154 offset:5120
	ds_read_b128 v[208:211], v154 offset:6144
	ds_read_b128 v[212:215], v154 offset:7168
	global_load_lds_dwordx4 v[216:217], off
	v_lshl_add_u64 v[216:217], vcc, 0, v[150:151]
	s_add_i32 m0, s1, 0xe000
	s_nop 0
	global_load_lds_dwordx4 v[216:217], off
	s_waitcnt lgkmcnt(8)
	s_barrier
	s_waitcnt lgkmcnt(0)
	s_setprio 1
	s_waitcnt lgkmcnt(0)
	v_mfma_f32_16x16x32_bf16 v[126:129], v[156:159], v[172:175], v[126:129]
	v_mfma_f32_16x16x32_bf16 v[122:125], v[164:167], v[172:175], v[122:125]
	v_mfma_f32_16x16x32_bf16 v[118:121], v[156:159], v[192:195], v[118:121]
	v_mfma_f32_16x16x32_bf16 v[114:117], v[164:167], v[192:195], v[114:117]
	v_mfma_f32_16x16x32_bf16 v[102:105], v[156:159], v[200:203], v[102:105]
	v_mfma_f32_16x16x32_bf16 v[98:101], v[164:167], v[200:203], v[98:101]
	v_mfma_f32_16x16x32_bf16 v[86:89], v[156:159], v[208:211], v[86:89]
	v_mfma_f32_16x16x32_bf16 v[82:85], v[164:167], v[208:211], v[82:85]
	v_mfma_f32_16x16x32_bf16 v[126:129], v[160:163], v[188:191], v[126:129]
	v_mfma_f32_16x16x32_bf16 v[122:125], v[168:171], v[188:191], v[122:125]
	v_mfma_f32_16x16x32_bf16 v[118:121], v[160:163], v[196:199], v[118:121]
	v_mfma_f32_16x16x32_bf16 v[114:117], v[168:171], v[196:199], v[114:117]
	v_mfma_f32_16x16x32_bf16 v[102:105], v[160:163], v[204:207], v[102:105]
	v_mfma_f32_16x16x32_bf16 v[98:101], v[168:171], v[204:207], v[98:101]
	v_mfma_f32_16x16x32_bf16 v[86:89], v[160:163], v[212:215], v[86:89]
	v_mfma_f32_16x16x32_bf16 v[82:85], v[168:171], v[212:215], v[82:85]
	s_setprio 0
	s_barrier
	s_add_i32 s23, 16, 0x14000
	s_add_i32 s20, s22, s9
	v_add_u32_e32 v155, s23, v152
	v_lshl_add_u64 v[232:233], s[66:67], 0, v[144:145]
	s_mov_b32 m0, s20
	ds_read_b128 v[216:219], v155
	ds_read_b128 v[220:223], v155 offset:1024
	ds_read_b128 v[224:227], v155 offset:2048
	ds_read_b128 v[228:231], v155 offset:3072
	global_load_lds_dwordx4 v[232:233], off
	v_lshl_add_u64 v[234:235], s[66:67], 0, v[140:141]
	s_add_i32 m0, s20, 0x2000
	s_nop 0
	global_load_lds_dwordx4 v[234:235], off
	s_barrier
	s_waitcnt lgkmcnt(0)
	s_setprio 1
	s_waitcnt lgkmcnt(0)
	v_mfma_f32_16x16x32_bf16 v[110:113], v[216:219], v[172:175], v[110:113]
	v_mfma_f32_16x16x32_bf16 v[106:109], v[224:227], v[172:175], v[106:109]
	v_mfma_f32_16x16x32_bf16 v[94:97], v[216:219], v[192:195], v[94:97]
	v_mfma_f32_16x16x32_bf16 v[90:93], v[224:227], v[192:195], v[90:93]
	v_mfma_f32_16x16x32_bf16 v[78:81], v[216:219], v[200:203], v[78:81]
	v_mfma_f32_16x16x32_bf16 v[74:77], v[224:227], v[200:203], v[74:77]
	v_mfma_f32_16x16x32_bf16 v[70:73], v[216:219], v[208:211], v[70:73]
	v_mfma_f32_16x16x32_bf16 v[66:69], v[224:227], v[208:211], v[66:69]
	v_mfma_f32_16x16x32_bf16 v[110:113], v[220:223], v[188:191], v[110:113]
	v_mfma_f32_16x16x32_bf16 v[106:109], v[228:231], v[188:191], v[106:109]
	v_mfma_f32_16x16x32_bf16 v[94:97], v[220:223], v[196:199], v[94:97]
	v_mfma_f32_16x16x32_bf16 v[90:93], v[228:231], v[196:199], v[90:93]
	v_mfma_f32_16x16x32_bf16 v[78:81], v[220:223], v[204:207], v[78:81]
	v_mfma_f32_16x16x32_bf16 v[74:77], v[228:231], v[204:207], v[74:77]
	v_mfma_f32_16x16x32_bf16 v[70:73], v[220:223], v[212:215], v[70:73]
	v_mfma_f32_16x16x32_bf16 v[66:69], v[228:231], v[212:215], v[66:69]
	s_setprio 0
	s_mov_b32 m0, s1
	v_lshl_add_u64 v[236:237], s[72:73], 0, v[146:147]
	s_barrier
	ds_read_b128 v[172:175], v154 offset:16384
	ds_read_b128 v[188:191], v154 offset:17408
	ds_read_b128 v[192:195], v154 offset:18432
	ds_read_b128 v[196:199], v154 offset:19456
	ds_read_b128 v[200:203], v154 offset:20480
	ds_read_b128 v[204:207], v154 offset:21504
	ds_read_b128 v[208:211], v154 offset:22528
	ds_read_b128 v[212:215], v154 offset:23552
	global_load_lds_dwordx4 v[236:237], off
	v_lshl_add_u64 v[238:239], s[72:73], 0, v[142:143]
	s_mov_b32 m0, s11
	s_nop 0
	global_load_lds_dwordx4 v[238:239], off
	s_barrier
	s_waitcnt lgkmcnt(0)
	s_setprio 1
	s_waitcnt lgkmcnt(0)
	v_mfma_f32_16x16x32_bf16 v[62:65], v[156:159], v[172:175], v[62:65]
	v_mfma_f32_16x16x32_bf16 v[58:61], v[164:167], v[172:175], v[58:61]
	v_mfma_f32_16x16x32_bf16 v[54:57], v[156:159], v[192:195], v[54:57]
	v_mfma_f32_16x16x32_bf16 v[50:53], v[164:167], v[192:195], v[50:53]
	v_mfma_f32_16x16x32_bf16 v[38:41], v[156:159], v[200:203], v[38:41]
	v_mfma_f32_16x16x32_bf16 v[34:37], v[164:167], v[200:203], v[34:37]
	v_mfma_f32_16x16x32_bf16 v[22:25], v[156:159], v[208:211], v[22:25]
	v_mfma_f32_16x16x32_bf16 v[18:21], v[164:167], v[208:211], v[18:21]
	v_mfma_f32_16x16x32_bf16 v[62:65], v[160:163], v[188:191], v[62:65]
	v_mfma_f32_16x16x32_bf16 v[58:61], v[168:171], v[188:191], v[58:61]
	v_mfma_f32_16x16x32_bf16 v[54:57], v[160:163], v[196:199], v[54:57]
	v_mfma_f32_16x16x32_bf16 v[50:53], v[168:171], v[196:199], v[50:53]
	v_mfma_f32_16x16x32_bf16 v[38:41], v[160:163], v[204:207], v[38:41]
	v_mfma_f32_16x16x32_bf16 v[34:37], v[168:171], v[204:207], v[34:37]
	v_mfma_f32_16x16x32_bf16 v[22:25], v[160:163], v[212:215], v[22:25]
	v_mfma_f32_16x16x32_bf16 v[18:21], v[168:171], v[212:215], v[18:21]
	s_setprio 0
	s_barrier
	s_add_u32 s20, s66, 0x40000
	s_addc_u32 s21, s67, 0
	s_add_i32 s22, s23, s9
	v_lshl_add_u64 v[156:157], s[20:21], 0, v[144:145]
	s_mov_b32 m0, s22
	s_nop 0
	global_load_lds_dwordx4 v[156:157], off
	v_lshl_add_u64 v[156:157], s[20:21], 0, v[140:141]
	s_add_i32 m0, s22, 0x2000
	s_nop 0
	global_load_lds_dwordx4 v[156:157], off
	s_cmp_eq_u32 s98, 0
	s_cbranch_scc1 .Lgdr512_n
	s_waitcnt vmcnt(24)
	s_mov_b32 s98, 0
	s_branch .Lgdr512_j

; #define PG8_STAGE(bufoff, gbase, voff) do { _Pragma("unroll") for (int _i = 0; _i < 2; ++_i) \
;         __builtin_amdgcn_global_load_lds((const unsigned*)((const char*)(gbase) + (voff)[_i]), (LAS unsigned*)(lds + (bufoff) + ldsw + _i * 8192), 16, 0, 0); } while (0)
; #define PG8_LDA(dst, b, h) do { _Pragma("unroll") for (int m = 0; m < 4; ++m) _Pragma("unroll") for (int k = 0; k < 2; ++k) dst[m][k] = *(const LAS bf16x8*)(lds + PG8_SA(b, h) + aoff + m * 2048 + k * 1024); } while (0)
; #define PG8_LDB(dst, b, h) do { _Pragma("unroll") for (int n = 0; n < 2; ++n) _Pragma("unroll") for (int k = 0; k < 2; ++k) dst[n][k] = *(const LAS bf16x8*)(lds + PG8_SB(b, h) + boff + n * 2048 + k * 1024); } while (0)
; #define PG8_MMA(ai, bj, At, Bt) do { __builtin_amdgcn_s_setprio(1); _Pragma("unroll") for (int m = 0; m < 4; ++m) _Pragma("unroll") for (int n = 0; n < 2; ++n) _Pragma("unroll") for (int k = 0; k < 2; ++k) \
;         acc[ai][bj][m][n] = __builtin_amdgcn_mfma_f32_16x16x32_bf16(Bt[n][k], At[m][k], acc[ai][bj][m][n], 0, 0, 0); __builtin_amdgcn_s_setprio(0); } while (0)
; #define PG8_WAIT_V(n) asm volatile("s_waitcnt vmcnt(" #n ")" ::: "memory")
; #define PG8_WAIT_L(n) asm volatile("s_waitcnt lgkmcnt(" #n ")" ::: "memory")
; #define PG8_BAR __builtin_amdgcn_s_barrier()
; #define PG8_SCHED __builtin_amdgcn_sched_barrier(0)
; template <class Epi, class Sched>
; __device__ __forceinline__ void gemm_phase(LAS unsigned char* lds, const Gemm g, const Sched& S, const Epi& E) {
;     ...
;             PG8_WAIT_V(6); PG8_BAR; PG8_MMA(1, 1, At, B1); PG8_BAR;
;             PG8_LDB(B0, 1, 0); PG8_SCHED; PG8_LDA(At, 1, 0); PG8_STAGE(PG8_SA(0, 1), a2 + hstep, voffA);
;             PG8_WAIT_L(8); PG8_BAR; PG8_WAIT_L(0); PG8_MMA(0, 0, At, B0); PG8_BAR; PG8_SCHED;
;             PG8_LDB(B1, 1, 1); PG8_STAGE(PG8_SB(1, 0), b3, voffB);
;             PG8_BAR; PG8_WAIT_L(0); PG8_MMA(0, 1, At, B1); PG8_BAR;
;             PG8_LDA(At, 1, 1); PG8_STAGE(PG8_SA(1, 0), a3, voffA);
;             PG8_BAR; PG8_WAIT_L(0); PG8_MMA(1, 0, At, B0); PG8_BAR; PG8_SCHED;
.Lgdr512_j:
	s_barrier
	s_setprio 1
	v_mfma_f32_16x16x32_bf16 v[46:49], v[216:219], v[172:175], v[46:49]
	v_mfma_f32_16x16x32_bf16 v[42:45], v[224:227], v[172:175], v[42:45]
	v_mfma_f32_16x16x32_bf16 v[30:33], v[216:219], v[192:195], v[30:33]
	v_mfma_f32_16x16x32_bf16 v[26:29], v[224:227], v[192:195], v[26:29]
	v_mfma_f32_16x16x32_bf16 v[14:17], v[216:219], v[200:203], v[14:17]
	v_mfma_f32_16x16x32_bf16 v[10:13], v[224:227], v[200:203], v[10:13]
	v_mfma_f32_16x16x32_bf16 v[4:7], v[216:219], v[208:211], v[4:7]
	v_mfma_f32_16x16x32_bf16 v[0:3], v[224:227], v[208:211], v[0:3]
	v_mfma_f32_16x16x32_bf16 v[46:49], v[220:223], v[188:191], v[46:49]
	v_mfma_f32_16x16x32_bf16 v[42:45], v[228:231], v[188:191], v[42:45]
	v_mfma_f32_16x16x32_bf16 v[30:33], v[220:223], v[196:199], v[30:33]
	v_mfma_f32_16x16x32_bf16 v[26:29], v[228:231], v[196:199], v[26:29]
	v_mfma_f32_16x16x32_bf16 v[14:17], v[220:223], v[204:207], v[14:17]
	v_mfma_f32_16x16x32_bf16 v[10:13], v[228:231], v[204:207], v[10:13]
	v_mfma_f32_16x16x32_bf16 v[4:7], v[220:223], v[212:215], v[4:7]
	v_mfma_f32_16x16x32_bf16 v[0:3], v[228:231], v[212:215], v[0:3]
	s_setprio 0
	s_add_i32 s22, 16, 0x18000
	v_add_u32_e32 v155, s22, v152
	s_barrier
	ds_read_b128 v[156:159], v155
	ds_read_b128 v[160:163], v155 offset:1024
	ds_read_b128 v[164:167], v155 offset:2048
	ds_read_b128 v[168:171], v155 offset:3072
	s_add_u32 s20, s72, 0x40000
	s_addc_u32 s21, s73, 0
	s_mov_b32 m0, s41
	v_lshl_add_u64 v[216:217], s[20:21], 0, v[146:147]
	ds_read_b128 v[172:175], v154 offset:32768
	ds_read_b128 v[188:191], v154 offset:33792
	ds_read_b128 v[192:195], v154 offset:34816
	ds_read_b128 v[196:199], v154 offset:35840
	ds_read_b128 v[200:203], v154 offset:36864
	ds_read_b128 v[204:207], v154 offset:37888
	ds_read_b128 v[208:211], v154 offset:38912
	ds_read_b128 v[212:215], v154 offset:39936
	global_load_lds_dwordx4 v[216:217], off
	v_lshl_add_u64 v[216:217], s[20:21], 0, v[142:143]
	s_mov_b32 m0, s12
	s_nop 0
	global_load_lds_dwordx4 v[216:217], off
	s_waitcnt lgkmcnt(8)
	s_barrier
	s_waitcnt lgkmcnt(0)
	s_setprio 1
	s_waitcnt lgkmcnt(0)
	v_mfma_f32_16x16x32_bf16 v[126:129], v[156:159], v[172:175], v[126:129]
	v_mfma_f32_16x16x32_bf16 v[122:125], v[164:167], v[172:175], v[122:125]
	v_mfma_f32_16x16x32_bf16 v[118:121], v[156:159], v[192:195], v[118:121]
	v_mfma_f32_16x16x32_bf16 v[114:117], v[164:167], v[192:195], v[114:117]
	v_mfma_f32_16x16x32_bf16 v[102:105], v[156:159], v[200:203], v[102:105]
	v_mfma_f32_16x16x32_bf16 v[98:101], v[164:167], v[200:203], v[98:101]
	v_mfma_f32_16x16x32_bf16 v[86:89], v[156:159], v[208:211], v[86:89]
	v_mfma_f32_16x16x32_bf16 v[82:85], v[164:167], v[208:211], v[82:85]
	v_mfma_f32_16x16x32_bf16 v[126:129], v[160:163], v[188:191], v[126:129]
	v_mfma_f32_16x16x32_bf16 v[122:125], v[168:171], v[188:191], v[122:125]
	v_mfma_f32_16x16x32_bf16 v[118:121], v[160:163], v[196:199], v[118:121]
	v_mfma_f32_16x16x32_bf16 v[114:117], v[168:171], v[196:199], v[114:117]
	v_mfma_f32_16x16x32_bf16 v[102:105], v[160:163], v[204:207], v[102:105]
	v_mfma_f32_16x16x32_bf16 v[98:101], v[168:171], v[204:207], v[98:101]
	v_mfma_f32_16x16x32_bf16 v[86:89], v[160:163], v[212:215], v[86:89]
	v_mfma_f32_16x16x32_bf16 v[82:85], v[168:171], v[212:215], v[82:85]
	s_setprio 0
	s_barrier
	s_add_i32 s23, 16, 0x1c000
	s_add_i32 s20, s22, s9
	v_add_u32_e32 v155, s23, v152
	v_lshl_add_u64 v[232:233], v[232:233], 0, s[94:95]
	s_mov_b32 m0, s20
	ds_read_b128 v[216:219], v155
	ds_read_b128 v[220:223], v155 offset:1024
	ds_read_b128 v[224:227], v155 offset:2048
	ds_read_b128 v[228:231], v155 offset:3072
	global_load_lds_dwordx4 v[232:233], off
	v_lshl_add_u64 v[232:233], v[234:235], 0, s[94:95]
	s_add_i32 m0, s20, 0x2000
	s_nop 0
	global_load_lds_dwordx4 v[232:233], off
	s_barrier
	s_waitcnt lgkmcnt(0)
	s_setprio 1
	s_waitcnt lgkmcnt(0)
	v_mfma_f32_16x16x32_bf16 v[110:113], v[216:219], v[172:175], v[110:113]
	v_mfma_f32_16x16x32_bf16 v[106:109], v[224:227], v[172:175], v[106:109]
	v_mfma_f32_16x16x32_bf16 v[94:97], v[216:219], v[192:195], v[94:97]
	v_mfma_f32_16x16x32_bf16 v[90:93], v[224:227], v[192:195], v[90:93]
	v_mfma_f32_16x16x32_bf16 v[78:81], v[216:219], v[200:203], v[78:81]
	v_mfma_f32_16x16x32_bf16 v[74:77], v[224:227], v[200:203], v[74:77]
	v_mfma_f32_16x16x32_bf16 v[70:73], v[216:219], v[208:211], v[70:73]
	v_mfma_f32_16x16x32_bf16 v[66:69], v[224:227], v[208:211], v[66:69]
	v_mfma_f32_16x16x32_bf16 v[110:113], v[220:223], v[188:191], v[110:113]
	v_mfma_f32_16x16x32_bf16 v[106:109], v[228:231], v[188:191], v[106:109]
	v_mfma_f32_16x16x32_bf16 v[94:97], v[220:223], v[196:199], v[94:97]
	v_mfma_f32_16x16x32_bf16 v[90:93], v[228:231], v[196:199], v[90:93]
	v_mfma_f32_16x16x32_bf16 v[78:81], v[220:223], v[204:207], v[78:81]
	v_mfma_f32_16x16x32_bf16 v[74:77], v[228:231], v[204:207], v[74:77]
	v_mfma_f32_16x16x32_bf16 v[70:73], v[220:223], v[212:215], v[70:73]
	v_mfma_f32_16x16x32_bf16 v[66:69], v[228:231], v[212:215], v[66:69]
	s_setprio 0
	s_mov_b32 m0, s13
	v_lshl_add_u64 v[232:233], v[236:237], 0, s[94:95]
	s_barrier
	ds_read_b128 v[172:175], v154 offset:49152
	ds_read_b128 v[188:191], v154 offset:50176
	ds_read_b128 v[192:195], v154 offset:51200
	ds_read_b128 v[196:199], v154 offset:52224
	ds_read_b128 v[200:203], v154 offset:53248
	ds_read_b128 v[204:207], v154 offset:54272
	ds_read_b128 v[208:211], v154 offset:55296
	ds_read_b128 v[212:215], v154 offset:56320
	global_load_lds_dwordx4 v[232:233], off
	v_lshl_add_u64 v[232:233], v[238:239], 0, s[94:95]
	s_mov_b32 m0, s14
	s_nop 0
	global_load_lds_dwordx4 v[232:233], off
	s_barrier
; #define PG8_STAGE(bufoff, gbase, voff) do { _Pragma("unroll") for (int _i = 0; _i < 2; ++_i) \
;         __builtin_amdgcn_global_load_lds((const unsigned*)((const char*)(gbase) + (voff)[_i]), (LAS unsigned*)(lds + (bufoff) + ldsw + _i * 8192), 16, 0, 0); } while (0)
; #define PG8_MMA(ai, bj, At, Bt) do { __builtin_amdgcn_s_setprio(1); _Pragma("unroll") for (int m = 0; m < 4; ++m) _Pragma("unroll") for (int n = 0; n < 2; ++n) _Pragma("unroll") for (int k = 0; k < 2; ++k) \
;         acc[ai][bj][m][n] = __builtin_amdgcn_mfma_f32_16x16x32_bf16(Bt[n][k], At[m][k], acc[ai][bj][m][n], 0, 0, 0); __builtin_amdgcn_s_setprio(0); } while (0)
; #define PG8_WAIT_V(n) asm volatile("s_waitcnt vmcnt(" #n ")" ::: "memory")
; #define PG8_WAIT_L(n) asm volatile("s_waitcnt lgkmcnt(" #n ")" ::: "memory")
; #define PG8_BAR __builtin_amdgcn_s_barrier()
; #define PG8_SCHED __builtin_amdgcn_sched_barrier(0)
; template <class Epi, class Sched>
; __device__ __forceinline__ void gemm_phase(LAS unsigned char* lds, const Gemm g, const Sched& S, const Epi& E) {
;     ...
;             PG8_BAR; PG8_WAIT_L(0); PG8_MMA(1, 0, At, B0); PG8_BAR; PG8_SCHED;
;             PG8_STAGE(PG8_SB(1, 1), b3 + hstep, voffB);
;             PG8_WAIT_V(6); PG8_BAR; PG8_MMA(1, 1, At, B1); PG8_BAR;
;         }
	s_waitcnt lgkmcnt(0)
	s_setprio 1
	s_waitcnt lgkmcnt(0)
	v_mfma_f32_16x16x32_bf16 v[62:65], v[156:159], v[172:175], v[62:65]
	v_mfma_f32_16x16x32_bf16 v[58:61], v[164:167], v[172:175], v[58:61]
	v_mfma_f32_16x16x32_bf16 v[54:57], v[156:159], v[192:195], v[54:57]
	v_mfma_f32_16x16x32_bf16 v[50:53], v[164:167], v[192:195], v[50:53]
	v_mfma_f32_16x16x32_bf16 v[38:41], v[156:159], v[200:203], v[38:41]
	v_mfma_f32_16x16x32_bf16 v[34:37], v[164:167], v[200:203], v[34:37]
	v_mfma_f32_16x16x32_bf16 v[22:25], v[156:159], v[208:211], v[22:25]
	v_mfma_f32_16x16x32_bf16 v[18:21], v[164:167], v[208:211], v[18:21]
	v_mfma_f32_16x16x32_bf16 v[62:65], v[160:163], v[188:191], v[62:65]
	v_mfma_f32_16x16x32_bf16 v[58:61], v[168:171], v[188:191], v[58:61]
	v_mfma_f32_16x16x32_bf16 v[54:57], v[160:163], v[196:199], v[54:57]
	v_mfma_f32_16x16x32_bf16 v[50:53], v[168:171], v[196:199], v[50:53]
	v_mfma_f32_16x16x32_bf16 v[38:41], v[160:163], v[204:207], v[38:41]
	v_mfma_f32_16x16x32_bf16 v[34:37], v[168:171], v[204:207], v[34:37]
	v_mfma_f32_16x16x32_bf16 v[22:25], v[160:163], v[212:215], v[22:25]
	v_mfma_f32_16x16x32_bf16 v[18:21], v[168:171], v[212:215], v[18:21]
	s_setprio 0
	s_barrier
	s_add_u32 s20, s66, 0x40080
	s_addc_u32 s21, s67, 0
	s_add_i32 s22, s23, s9
	v_lshl_add_u64 v[156:157], s[20:21], 0, v[144:145]
	s_mov_b32 m0, s22
	s_nop 0
	global_load_lds_dwordx4 v[156:157], off
	v_lshl_add_u64 v[156:157], s[20:21], 0, v[140:141]
	s_add_i32 m0, s22, 0x2000
	s_nop 0
	global_load_lds_dwordx4 v[156:157], off
	s_waitcnt vmcnt(6)
	s_barrier
	s_setprio 1
	v_mfma_f32_16x16x32_bf16 v[46:49], v[216:219], v[172:175], v[46:49]
	v_mfma_f32_16x16x32_bf16 v[42:45], v[224:227], v[172:175], v[42:45]
	v_mfma_f32_16x16x32_bf16 v[30:33], v[216:219], v[192:195], v[30:33]
	v_mfma_f32_16x16x32_bf16 v[26:29], v[224:227], v[192:195], v[26:29]
	v_mfma_f32_16x16x32_bf16 v[14:17], v[216:219], v[200:203], v[14:17]
	v_mfma_f32_16x16x32_bf16 v[10:13], v[224:227], v[200:203], v[10:13]
	v_mfma_f32_16x16x32_bf16 v[4:7], v[216:219], v[208:211], v[4:7]
	v_mfma_f32_16x16x32_bf16 v[0:3], v[224:227], v[208:211], v[0:3]
	v_mfma_f32_16x16x32_bf16 v[46:49], v[220:223], v[188:191], v[46:49]
	v_mfma_f32_16x16x32_bf16 v[42:45], v[228:231], v[188:191], v[42:45]
	v_mfma_f32_16x16x32_bf16 v[30:33], v[220:223], v[196:199], v[30:33]
	v_mfma_f32_16x16x32_bf16 v[26:29], v[228:231], v[196:199], v[26:29]
	v_mfma_f32_16x16x32_bf16 v[14:17], v[220:223], v[204:207], v[14:17]
	v_mfma_f32_16x16x32_bf16 v[10:13], v[228:231], v[204:207], v[10:13]
	v_mfma_f32_16x16x32_bf16 v[4:7], v[220:223], v[212:215], v[4:7]
	v_mfma_f32_16x16x32_bf16 v[0:3], v[228:231], v[212:215], v[0:3]
	s_setprio 0
	s_add_i32 s19, s19, 2
	s_add_u32 vcc_lo, vcc_lo, 0x100
	s_addc_u32 vcc_hi, vcc_hi, 0
	s_add_u32 s74, s74, 0x100
	s_addc_u32 s18, s18, 0
	s_cmp_gt_u32 s19, 13
	s_barrier
	s_cbranch_scc0 .LBB0_515
	s_cmp_lg_u64 s[38:39], 0
	s_cbranch_scc1 .Lgdr512_e
	s_add_u32 s100, s78, 0x40080
	s_addc_u32 s101, s79, 0
	v_lshl_add_u64 v[216:217], s[100:101], 0, v[148:149]
	s_add_i32 m0, s1, 0xc000
	s_nop 0
	global_load_lds_dwordx4 v[216:217], off
	v_lshl_add_u64 v[216:217], s[100:101], 0, v[150:151]
	s_add_i32 m0, s1, 0xe000
	s_nop 0
	global_load_lds_dwordx4 v[216:217], off
	s_mov_b32 s98, 1
; __device__ __forceinline__ unsigned pk_bf16(float a, float b) { f32x2 v = {a, b}; bf2_t r = __builtin_convertvector(v, bf2_t); return __builtin_bit_cast(unsigned, r); }
; #define PG8_WAIT_V(n) asm volatile("s_waitcnt vmcnt(" #n ")" ::: "memory")
; #define PG8_BAR __builtin_amdgcn_s_barrier()
;     __device__ __forceinline__ void operator()(const f32x4 (&acc)[2][2][4][2], const Unit& u, int wr, int wc, int fr, int fq) const {
;         const int row0 = u.pm * BM + wr * 64 + fr; int colt = u.pn * BM; bf16_t* base = O;
;         if (split_cols) { const int t = colt / split_cols; base += (size_t)t * split_stride; colt -= t * split_cols; }
;         const int col0 = colt + wc * 32 + 8 * fq;
; #pragma unroll
;         for (int ai = 0; ai < 2; ++ai)
; #pragma unroll
;             for (int m = 0; m < 4; ++m) { const int row = row0 + ai * HALF + m * 16;
;                 bf16_t* rowp = slot_stride ? base + (size_t)(colt >> 7) * slot_stride + (size_t)row * 128 + wc * 32 + 8 * fq : base + (size_t)row * ldc + col0;
; #pragma unroll
;                 for (int bj = 0; bj < 2; ++bj) { const f32x4 v0 = acc[ai][bj][m][0], v1 = acc[ai][bj][m][1];
;                     u32x4 w; w.x = pk_bf16(v0[0], v0[1]); w.y = pk_bf16(v0[2], v0[3]); w.z = pk_bf16(v1[0], v1[1]); w.w = pk_bf16(v1[2], v1[3]);
;                     *(u32x4*)(rowp + (slot_stride ? (size_t)bj * slot_stride : (size_t)bj * HALF)) = w; } }
; template <class Epi, class Sched>
; __device__ __forceinline__ void gemm_phase(LAS unsigned char* lds, const Gemm g, const Sched& S, const Epi& E) {
;     ...
;         E(acc, cur, wr, wc, fr, fq); S.done(cur);
;         if (!has_next) break;
; #pragma unroll
;         for (int a = 0; a < 2; ++a)
; #pragma unroll
;             for (int b = 0; b < 2; ++b)
; #pragma unroll
;                 for (int m = 0; m < 4; ++m)
; #pragma unroll
;                     for (int n = 0; n < 2; ++n) acc[a][b][m][n] = (f32x4){0.f, 0.f, 0.f, 0.f};
;         cur = nxt; cA = nA; cB = nB; ++ui;
;     }
;     PG8_WAIT_V(0);
;     if (wr == 0) PG8_BAR;
;     PG8_BAR;
.Lgdr512_e:
	v_lshl_add_u32 v156, s40, 8, v9
	v_lshl_or_b32 v158, s0, 8, v153
	v_ashrrev_i32_e32 v159, 31, v158
	v_ashrrev_i32_e32 v157, 31, v156
	v_lshl_add_u64 v[158:159], v[158:159], 1, s[82:83]
	v_lshlrev_b64 v[160:161], 11, v[156:157]
	v_lshl_add_u64 v[160:161], v[158:159], 0, v[160:161]
	s_mov_b32 s0, 0x40000
	s_mov_b64 s[16:17], 0x40000
	v_cvt_pk_bf16_f32 v62, v62, v63
	v_cvt_pk_bf16_f32 v63, v64, v65
	v_cvt_pk_bf16_f32 v64, v58, v59
	v_add_co_u32_e32 v58, vcc, s0, v160
	v_cvt_pk_bf16_f32 v70, v70, v71
	v_cvt_pk_bf16_f32 v71, v72, v73
	v_cvt_pk_bf16_f32 v72, v66, v67
	v_lshl_add_u64 v[66:67], v[160:161], 0, s[16:17]
	v_addc_co_u32_e32 v59, vcc, 0, v161, vcc
	v_cvt_pk_bf16_f32 v46, v46, v47
	v_cvt_pk_bf16_f32 v47, v48, v49
	v_cvt_pk_bf16_f32 v48, v42, v43
	v_cvt_pk_bf16_f32 v49, v44, v45
	s_mov_b32 s0, 0x48000
	global_store_dwordx4 v[66:67], v[46:49], off offset:256
	s_mov_b64 s[16:17], 0x48000
	v_cvt_pk_bf16_f32 v110, v110, v111
	v_add_co_u32_e32 v48, vcc, s0, v160
	v_cvt_pk_bf16_f32 v111, v112, v113
	v_cvt_pk_bf16_f32 v112, v106, v107
	v_or_b32_e32 v106, 16, v156
	v_lshl_add_u64 v[46:47], v[160:161], 0, s[16:17]
	v_addc_co_u32_e32 v49, vcc, 0, v161, vcc
	v_cvt_pk_bf16_f32 v30, v30, v31
	v_cvt_pk_bf16_f32 v31, v32, v33
	v_cvt_pk_bf16_f32 v32, v26, v27
	v_cvt_pk_bf16_f32 v33, v28, v29
	s_mov_b32 s0, 0x50000
	v_ashrrev_i32_e32 v107, 31, v106
	v_cvt_pk_bf16_f32 v94, v94, v95
	v_cvt_pk_bf16_f32 v95, v96, v97
	v_cvt_pk_bf16_f32 v96, v90, v91
	v_or_b32_e32 v90, 32, v156
	global_store_dwordx4 v[46:47], v[30:33], off offset:256
	s_mov_b64 s[16:17], 0x50000
	v_cvt_pk_bf16_f32 v113, v108, v109
	v_add_co_u32_e32 v32, vcc, s0, v160
	v_lshlrev_b64 v[106:107], 11, v[106:107]
	v_ashrrev_i32_e32 v91, 31, v90
	v_cvt_pk_bf16_f32 v78, v78, v79
	v_cvt_pk_bf16_f32 v79, v80, v81
	v_cvt_pk_bf16_f32 v80, v74, v75
	v_or_b32_e32 v74, 48, v156
	v_lshl_add_u64 v[30:31], v[160:161], 0, s[16:17]
	v_addc_co_u32_e32 v33, vcc, 0, v161, vcc
	v_cvt_pk_bf16_f32 v14, v14, v15
	v_cvt_pk_bf16_f32 v15, v16, v17
	v_cvt_pk_bf16_f32 v16, v10, v11
	v_cvt_pk_bf16_f32 v17, v12, v13
	s_mov_b32 s0, 0x58000
	global_store_dwordx4 v[160:161], v[110:113], off offset:256
	v_cvt_pk_bf16_f32 v97, v92, v93
	v_lshlrev_b64 v[90:91], 11, v[90:91]
	v_lshl_add_u64 v[110:111], v[158:159], 0, v[106:107]
	v_ashrrev_i32_e32 v75, 31, v74
	global_store_dwordx4 v[30:31], v[14:17], off offset:256
	global_store_dwordx4 v[110:111], v[94:97], off offset:256
	v_cvt_pk_bf16_f32 v81, v76, v77
	v_add_co_u32_e32 v16, vcc, s0, v160
	v_lshl_add_u64 v[94:95], v[158:159], 0, v[90:91]
	v_lshlrev_b64 v[74:75], 11, v[74:75]
	s_mov_b64 s[16:17], 0x58000
	v_addc_co_u32_e32 v17, vcc, 0, v161, vcc
	v_cvt_pk_bf16_f32 v126, v126, v127
	v_cvt_pk_bf16_f32 v127, v128, v129
	v_cvt_pk_bf16_f32 v128, v122, v123
	v_cvt_pk_bf16_f32 v129, v124, v125
	v_cvt_pk_bf16_f32 v106, v118, v119
	v_cvt_pk_bf16_f32 v107, v120, v121
	v_cvt_pk_bf16_f32 v108, v114, v115
	v_cvt_pk_bf16_f32 v109, v116, v117
	v_cvt_pk_bf16_f32 v90, v102, v103
	v_cvt_pk_bf16_f32 v91, v104, v105
	v_cvt_pk_bf16_f32 v92, v98, v99
	v_cvt_pk_bf16_f32 v93, v100, v101
	global_store_dwordx4 v[94:95], v[78:81], off offset:256
	v_cvt_pk_bf16_f32 v76, v82, v83
	v_cvt_pk_bf16_f32 v77, v84, v85
	v_lshl_add_u64 v[78:79], v[158:159], 0, v[74:75]
	v_cvt_pk_bf16_f32 v74, v86, v87
	v_cvt_pk_bf16_f32 v75, v88, v89
	v_cvt_pk_bf16_f32 v73, v68, v69
	v_cvt_pk_bf16_f32 v65, v60, v61
	v_cvt_pk_bf16_f32 v42, v54, v55
	v_cvt_pk_bf16_f32 v43, v56, v57
	v_cvt_pk_bf16_f32 v44, v50, v51
	v_cvt_pk_bf16_f32 v45, v52, v53
	v_cvt_pk_bf16_f32 v26, v38, v39
	v_cvt_pk_bf16_f32 v27, v40, v41
	v_cvt_pk_bf16_f32 v28, v34, v35
	v_cvt_pk_bf16_f32 v29, v36, v37
	v_lshl_add_u64 v[14:15], v[160:161], 0, s[16:17]
	v_cvt_pk_bf16_f32 v10, v22, v23
	v_cvt_pk_bf16_f32 v11, v24, v25
	v_cvt_pk_bf16_f32 v12, v18, v19
	v_cvt_pk_bf16_f32 v13, v20, v21
	v_cvt_pk_bf16_f32 v4, v4, v5
	v_cvt_pk_bf16_f32 v5, v6, v7
	v_cvt_pk_bf16_f32 v6, v0, v1
	v_cvt_pk_bf16_f32 v7, v2, v3
	s_and_b64 vcc, exec, s[38:39]
	s_mov_b32 s0, s42
	s_mov_b32 s40, s88
	s_mov_b64 s[74:75], s[70:71]
	s_mov_b64 s[72:73], s[78:79]
	global_store_dwordx4 v[160:161], v[126:129], off
	global_store_dwordx4 v[110:111], v[106:109], off
	global_store_dwordx4 v[94:95], v[90:93], off
	global_store_dwordx4 v[78:79], v[74:77], off
	global_store_dwordx4 v[78:79], v[70:73], off offset:256
	global_store_dwordx4 v[58:59], v[62:65], off
	global_store_dwordx4 v[48:49], v[42:45], off
	global_store_dwordx4 v[32:33], v[26:29], off
	global_store_dwordx4 v[16:17], v[10:13], off
	global_store_dwordx4 v[14:15], v[4:7], off offset:256
	s_cbranch_vccz .LBB0_512
	s_waitcnt vmcnt(0)
	s_cmpk_gt_u32 s6, 0xff
	s_cbranch_scc1 .LBB0_519
	s_barrier

; #define PG8_STAGE(bufoff, gbase, voff) do { _Pragma("unroll") for (int _i = 0; _i < 2; ++_i) \
;         __builtin_amdgcn_global_load_lds((const unsigned*)((const char*)(gbase) + (voff)[_i]), (LAS unsigned*)(lds + (bufoff) + ldsw + _i * 8192), 16, 0, 0); } while (0)
; #define PG8_WAIT_V(n) asm volatile("s_waitcnt vmcnt(" #n ")" ::: "memory")
; #define PG8_BAR __builtin_amdgcn_s_barrier()
; template <class Epi, class Sched>
; __device__ __forceinline__ void gemm_phase(LAS unsigned char* lds, const Gemm g, const Sched& S, const Epi& E) {
;     ...
;     for (int i = 0; i < 2; ++i) { int R, C; stage_rc(tid * 16 + i * 8192, R, C); const int Rb = Epi::PERM ? ((R & ~31) + perm32(R & 31)) : R;
;         voffA[i] = (unsigned)(R * K + C) * 2u; voffB[i] = (unsigned)(Rb * K + C) * 2u; }
;     const size_t kstep = (size_t)(BK * 2);
;     const size_t hstep = (size_t)HALF * K * 2;
;     const size_t tstep = 2 * hstep;
;     const unsigned ldsw = (unsigned)wid * 1024u;
;     const int aoff = lds_byte(wr * 64 + fr, fq * 8), boff = lds_byte(wc * 32 + fr, fq * 8);
;     ...
;     Unit cur, nxt; int ui = 0;
;     if (!S.next(0, cur)) return;
;     f32x4 acc[2][2][4][2];
; #pragma unroll
;     for (int a = 0; a < 2; ++a)
; #pragma unroll
;         for (int b = 0; b < 2; ++b)
; #pragma unroll
;             for (int m = 0; m < 4; ++m)
; #pragma unroll
;                 for (int n = 0; n < 2; ++n) acc[a][b][m][n] = (f32x4){0.f, 0.f, 0.f, 0.f};
;     bf16x8 At[4][2], B0[2][2], B1[2][2];
;     const char* cA = (const char*)g.A + (size_t)cur.pm * tstep; const char* cB = (const char*)g.Bt + (size_t)cur.pn * tstep;
;     S.a_ready(cur);
;     PG8_STAGE(PG8_SB(0, 0), cB, voffB); PG8_STAGE(PG8_SA(0, 0), cA, voffA); PG8_STAGE(PG8_SB(0, 1), cB + hstep, voffB); PG8_STAGE(PG8_SA(0, 1), cA + hstep, voffA);
;     if (wr == 1) PG8_BAR;
;     PG8_WAIT_V(4); PG8_BAR;
;     PG8_STAGE(PG8_SB(1, 0), cB + kstep, voffB); PG8_STAGE(PG8_SA(1, 0), cA + kstep, voffA); PG8_STAGE(PG8_SB(1, 1), cB + hstep + kstep, voffB);
;     PG8_WAIT_V(6); PG8_BAR;
.LBB0_642:
	v_lshrrev_b32_e32 v18, 1, v6
	v_and_b32_e32 v18, 24, v18
	s_lshl_b32 s1, s1, 5
	v_mov_b32_e32 v145, v8
	v_and_b32_e32 v7, 15, v6
	v_lshlrev_b32_e32 v19, 1, v18
	v_lshlrev_b32_e32 v6, 2, v6
	s_and_b32 s18, s1, 0x60
	v_lshl_add_u64 v[10:11], s[70:71], 0, v[144:145]
	v_mov_b32_e32 v141, v8
	v_lshl_or_b32 v9, s14, 6, v7
	v_lshl_or_b32 v7, v7, 6, v19
	s_lshl_b32 s14, s14, 13
	v_and_b32_e32 v6, 32, v6
	s_lshl_b32 s1, s18, 7
	v_lshl_add_u64 v[12:13], s[70:71], 0, v[140:141]
	v_mov_b32_e32 v147, v8
	v_bitop3_b32 v19, v7, s14, v6 bitop3:0xde
	v_bitop3_b32 v152, v7, s1, v6 bitop3:0xde
	s_add_i32 m0, s11, 0x18000
	v_lshl_add_u64 v[6:7], v[10:11], 0, s[94:95]
	v_lshl_add_u64 v[14:15], s[78:79], 0, v[146:147]
	v_mov_b32_e32 v143, v8
	s_waitcnt vmcnt(4)
	s_barrier
	global_load_lds_dwordx4 v[6:7], off
	v_lshl_add_u64 v[6:7], v[12:13], 0, s[94:95]
	s_add_i32 m0, s11, 0x1a000
	s_add_i32 s14, s11, 0x8000
	s_add_i32 s15, s11, 0xa000
	v_lshl_add_u64 v[16:17], s[78:79], 0, v[142:143]
	global_load_lds_dwordx4 v[6:7], off
	v_lshl_add_u64 v[6:7], v[14:15], 0, s[94:95]
	s_mov_b32 m0, s14
	s_add_u32 s16, s70, 0x40080
	global_load_lds_dwordx4 v[6:7], off
	v_lshl_add_u64 v[6:7], v[16:17], 0, s[94:95]
	s_mov_b32 m0, s15
	s_addc_u32 s17, s71, 0
	global_load_lds_dwordx4 v[6:7], off
	s_add_i32 m0, s11, 0x1c000
	v_lshl_add_u64 v[6:7], s[16:17], 0, v[144:145]
	global_load_lds_dwordx4 v[6:7], off
	v_lshl_add_u64 v[6:7], s[16:17], 0, v[140:141]
	s_add_i32 m0, s11, 0x1e000
	s_mov_b32 s1, s3
	global_load_lds_dwordx4 v[6:7], off
	v_lshlrev_b32_e32 v6, 14, v4
	v_and_b32_e32 v6, 0xffff8000, v6
	v_lshl_add_u32 v3, v3, 11, v6
	v_and_b32_e32 v4, 1, v4
	v_lshl_or_b32 v3, v4, 6, v3
	v_lshl_add_u32 v148, v5, 1, v3
	v_lshlrev_b32_e32 v3, 14, v0
	v_and_b32_e32 v3, 0xffff8000, v3
	s_waitcnt vmcnt(6)
	v_lshl_add_u32 v1, v1, 11, v3
	v_and_b32_e32 v0, 1, v0
	v_lshl_or_b32 v0, v0, 6, v1
	v_or_b32_e32 v153, s18, v18
	v_mov_b32_e32 v149, v8
	v_lshl_add_u32 v150, v2, 1, v0
	v_mov_b32_e32 v151, v8
	s_mov_b32 s43, 0
	v_add_u32_e32 v154, 16, v19
	s_barrier
	s_mov_b32 s98, 0

; #define PG8_STAGE(bufoff, gbase, voff) do { _Pragma("unroll") for (int _i = 0; _i < 2; ++_i) \
;         __builtin_amdgcn_global_load_lds((const unsigned*)((const char*)(gbase) + (voff)[_i]), (LAS unsigned*)(lds + (bufoff) + ldsw + _i * 8192), 16, 0, 0); } while (0)
; #define PG8_LDA(dst, b, h) do { _Pragma("unroll") for (int m = 0; m < 4; ++m) _Pragma("unroll") for (int k = 0; k < 2; ++k) dst[m][k] = *(const LAS bf16x8*)(lds + PG8_SA(b, h) + aoff + m * 2048 + k * 1024); } while (0)
; #define PG8_LDB(dst, b, h) do { _Pragma("unroll") for (int n = 0; n < 2; ++n) _Pragma("unroll") for (int k = 0; k < 2; ++k) dst[n][k] = *(const LAS bf16x8*)(lds + PG8_SB(b, h) + boff + n * 2048 + k * 1024); } while (0)
; #define PG8_MMA(ai, bj, At, Bt) do { __builtin_amdgcn_s_setprio(1); _Pragma("unroll") for (int m = 0; m < 4; ++m) _Pragma("unroll") for (int n = 0; n < 2; ++n) _Pragma("unroll") for (int k = 0; k < 2; ++k) \
;         acc[ai][bj][m][n] = __builtin_amdgcn_mfma_f32_16x16x32_bf16(Bt[n][k], At[m][k], acc[ai][bj][m][n], 0, 0, 0); __builtin_amdgcn_s_setprio(0); } while (0)
; #define PG8_WAIT_L(n) asm volatile("s_waitcnt lgkmcnt(" #n ")" ::: "memory")
; #define PG8_BAR __builtin_amdgcn_s_barrier()
; #define PG8_SCHED __builtin_amdgcn_sched_barrier(0)
; template <class Epi, class Sched>
; __device__ __forceinline__ void gemm_phase(LAS unsigned char* lds, const Gemm g, const Sched& S, const Epi& E) {
;     ...
;         for (int t = 0; t < nt; t += 2) {
;             const bool last = (t == nt - 2);
;             const char* a1 = cA + (size_t)(t + 1) * kstep;
;             const char* a2 = last ? nA : cA + (size_t)(t + 2) * kstep; const char* b2 = last ? nB : cB + (size_t)(t + 2) * kstep;
;             const char* a3 = a2 + kstep; const char* b3 = b2 + kstep;
;             if (last && has_next) S.a_ready(nxt);
;             PG8_LDB(B0, 0, 0); PG8_SCHED; PG8_LDA(At, 0, 0); PG8_STAGE(PG8_SA(1, 1), a1 + hstep, voffA);
;             PG8_WAIT_L(8); PG8_BAR; PG8_WAIT_L(0); PG8_MMA(0, 0, At, B0); PG8_BAR; PG8_SCHED;
;             PG8_LDB(B1, 0, 1); PG8_STAGE(PG8_SB(0, 0), b2, voffB);
;             PG8_BAR; PG8_WAIT_L(0); PG8_MMA(0, 1, At, B1); PG8_BAR;
;             PG8_LDA(At, 0, 1); PG8_STAGE(PG8_SA(0, 0), a2, voffA);
;             PG8_BAR; PG8_WAIT_L(0); PG8_MMA(1, 0, At, B0); PG8_BAR; PG8_SCHED;
;             PG8_STAGE(PG8_SB(0, 1), b2 + hstep, voffB);
.LBB0_646:
	s_add_u32 s21, vcc_lo, 0xfffc0080
	s_addc_u32 s22, vcc_hi, -1
	s_add_i32 s23, 16, 0x10000
	v_add_u32_e32 v155, s23, v152
	ds_read_b128 v[156:159], v155
	ds_read_b128 v[160:163], v155 offset:1024
	ds_read_b128 v[164:167], v155 offset:2048
	ds_read_b128 v[168:171], v155 offset:3072
	s_cmp_eq_u32 s20, 12
	s_cselect_b32 s79, s75, s22
	s_cselect_b32 s78, s16, s21
	s_cselect_b32 s71, s17, s19
	s_cselect_b32 s70, s73, s18
	v_lshl_add_u64 v[216:217], vcc, 0, v[148:149]
	s_add_i32 m0, s11, 0xc000
	ds_read_b128 v[172:175], v154
	ds_read_b128 v[188:191], v154 offset:1024
	ds_read_b128 v[192:195], v154 offset:2048
	ds_read_b128 v[196:199], v154 offset:3072
	ds_read_b128 v[200:203], v154 offset:4096
	ds_read_b128 v[204:207], v154 offset:5120
	ds_read_b128 v[208:211], v154 offset:6144
	ds_read_b128 v[212:215], v154 offset:7168
	global_load_lds_dwordx4 v[216:217], off
	v_lshl_add_u64 v[216:217], vcc, 0, v[150:151]
	s_add_i32 m0, s11, 0xe000
	s_nop 0
	global_load_lds_dwordx4 v[216:217], off
	s_waitcnt lgkmcnt(8)
	s_barrier
	s_waitcnt lgkmcnt(0)
	s_setprio 1
	s_waitcnt lgkmcnt(0)
	v_mfma_f32_16x16x32_bf16 v[126:129], v[156:159], v[172:175], v[126:129]
	v_mfma_f32_16x16x32_bf16 v[122:125], v[164:167], v[172:175], v[122:125]
	v_mfma_f32_16x16x32_bf16 v[118:121], v[156:159], v[192:195], v[118:121]
	v_mfma_f32_16x16x32_bf16 v[114:117], v[164:167], v[192:195], v[114:117]
	v_mfma_f32_16x16x32_bf16 v[102:105], v[156:159], v[200:203], v[102:105]
	v_mfma_f32_16x16x32_bf16 v[98:101], v[164:167], v[200:203], v[98:101]
	v_mfma_f32_16x16x32_bf16 v[86:89], v[156:159], v[208:211], v[86:89]
	v_mfma_f32_16x16x32_bf16 v[82:85], v[164:167], v[208:211], v[82:85]
	v_mfma_f32_16x16x32_bf16 v[126:129], v[160:163], v[188:191], v[126:129]
	v_mfma_f32_16x16x32_bf16 v[122:125], v[168:171], v[188:191], v[122:125]
	v_mfma_f32_16x16x32_bf16 v[118:121], v[160:163], v[196:199], v[118:121]
	v_mfma_f32_16x16x32_bf16 v[114:117], v[168:171], v[196:199], v[114:117]
	v_mfma_f32_16x16x32_bf16 v[102:105], v[160:163], v[204:207], v[102:105]
	v_mfma_f32_16x16x32_bf16 v[98:101], v[168:171], v[204:207], v[98:101]
	v_mfma_f32_16x16x32_bf16 v[86:89], v[160:163], v[212:215], v[86:89]
	v_mfma_f32_16x16x32_bf16 v[82:85], v[168:171], v[212:215], v[82:85]
	s_setprio 0
	s_barrier
	s_add_i32 s21, 16, 0x14000
	s_add_i32 s22, s23, s9
	v_add_u32_e32 v155, s21, v152
	v_lshl_add_u64 v[232:233], s[70:71], 0, v[144:145]
	s_mov_b32 m0, s22
	ds_read_b128 v[216:219], v155
	ds_read_b128 v[220:223], v155 offset:1024
	ds_read_b128 v[224:227], v155 offset:2048
	ds_read_b128 v[228:231], v155 offset:3072
	global_load_lds_dwordx4 v[232:233], off
	v_lshl_add_u64 v[234:235], s[70:71], 0, v[140:141]
	s_add_i32 m0, s22, 0x2000
	s_nop 0
	global_load_lds_dwordx4 v[234:235], off
	s_barrier
	s_waitcnt lgkmcnt(0)
	s_setprio 1
	s_waitcnt lgkmcnt(0)
	v_mfma_f32_16x16x32_bf16 v[110:113], v[216:219], v[172:175], v[110:113]
	v_mfma_f32_16x16x32_bf16 v[106:109], v[224:227], v[172:175], v[106:109]
	v_mfma_f32_16x16x32_bf16 v[94:97], v[216:219], v[192:195], v[94:97]
	v_mfma_f32_16x16x32_bf16 v[90:93], v[224:227], v[192:195], v[90:93]
	v_mfma_f32_16x16x32_bf16 v[78:81], v[216:219], v[200:203], v[78:81]
	v_mfma_f32_16x16x32_bf16 v[74:77], v[224:227], v[200:203], v[74:77]
	v_mfma_f32_16x16x32_bf16 v[70:73], v[216:219], v[208:211], v[70:73]
	v_mfma_f32_16x16x32_bf16 v[66:69], v[224:227], v[208:211], v[66:69]
	v_mfma_f32_16x16x32_bf16 v[110:113], v[220:223], v[188:191], v[110:113]
	v_mfma_f32_16x16x32_bf16 v[106:109], v[228:231], v[188:191], v[106:109]
	v_mfma_f32_16x16x32_bf16 v[94:97], v[220:223], v[196:199], v[94:97]
	v_mfma_f32_16x16x32_bf16 v[90:93], v[228:231], v[196:199], v[90:93]
	v_mfma_f32_16x16x32_bf16 v[78:81], v[220:223], v[204:207], v[78:81]
	v_mfma_f32_16x16x32_bf16 v[74:77], v[228:231], v[204:207], v[74:77]
	v_mfma_f32_16x16x32_bf16 v[70:73], v[220:223], v[212:215], v[70:73]
	v_mfma_f32_16x16x32_bf16 v[66:69], v[228:231], v[212:215], v[66:69]
	s_setprio 0
	s_mov_b32 m0, s11
	v_lshl_add_u64 v[236:237], s[78:79], 0, v[146:147]
	s_barrier
	ds_read_b128 v[172:175], v154 offset:16384
	ds_read_b128 v[188:191], v154 offset:17408
	ds_read_b128 v[192:195], v154 offset:18432
	ds_read_b128 v[196:199], v154 offset:19456
	ds_read_b128 v[200:203], v154 offset:20480
	ds_read_b128 v[204:207], v154 offset:21504
	ds_read_b128 v[208:211], v154 offset:22528
	ds_read_b128 v[212:215], v154 offset:23552
	global_load_lds_dwordx4 v[236:237], off
	v_lshl_add_u64 v[238:239], s[78:79], 0, v[142:143]
	s_mov_b32 m0, s41
	s_nop 0
	global_load_lds_dwordx4 v[238:239], off
	s_barrier
	s_waitcnt lgkmcnt(0)
	s_setprio 1
	s_waitcnt lgkmcnt(0)
	v_mfma_f32_16x16x32_bf16 v[62:65], v[156:159], v[172:175], v[62:65]
	v_mfma_f32_16x16x32_bf16 v[58:61], v[164:167], v[172:175], v[58:61]
	v_mfma_f32_16x16x32_bf16 v[54:57], v[156:159], v[192:195], v[54:57]
	v_mfma_f32_16x16x32_bf16 v[50:53], v[164:167], v[192:195], v[50:53]
	v_mfma_f32_16x16x32_bf16 v[38:41], v[156:159], v[200:203], v[38:41]
	v_mfma_f32_16x16x32_bf16 v[34:37], v[164:167], v[200:203], v[34:37]
	v_mfma_f32_16x16x32_bf16 v[22:25], v[156:159], v[208:211], v[22:25]
	v_mfma_f32_16x16x32_bf16 v[18:21], v[164:167], v[208:211], v[18:21]
	v_mfma_f32_16x16x32_bf16 v[62:65], v[160:163], v[188:191], v[62:65]
	v_mfma_f32_16x16x32_bf16 v[58:61], v[168:171], v[188:191], v[58:61]
	v_mfma_f32_16x16x32_bf16 v[54:57], v[160:163], v[196:199], v[54:57]
	v_mfma_f32_16x16x32_bf16 v[50:53], v[168:171], v[196:199], v[50:53]
	v_mfma_f32_16x16x32_bf16 v[38:41], v[160:163], v[204:207], v[38:41]
	v_mfma_f32_16x16x32_bf16 v[34:37], v[168:171], v[204:207], v[34:37]
	v_mfma_f32_16x16x32_bf16 v[22:25], v[160:163], v[212:215], v[22:25]
	v_mfma_f32_16x16x32_bf16 v[18:21], v[168:171], v[212:215], v[18:21]
	s_setprio 0
	s_barrier
	s_add_u32 s22, s70, 0x40000
	s_addc_u32 s23, s71, 0
	s_add_i32 s21, s21, s9
	v_lshl_add_u64 v[156:157], s[22:23], 0, v[144:145]
	s_mov_b32 m0, s21
	s_nop 0
	global_load_lds_dwordx4 v[156:157], off
	v_lshl_add_u64 v[156:157], s[22:23], 0, v[140:141]
	s_add_i32 m0, s21, 0x2000
	s_nop 0
	global_load_lds_dwordx4 v[156:157], off
	s_cmp_eq_u32 s98, 0
	s_cbranch_scc1 .Lgdr643_n
	s_waitcnt vmcnt(24)
	s_mov_b32 s98, 0
	s_branch .Lgdr643_j

; #define PG8_STAGE(bufoff, gbase, voff) do { _Pragma("unroll") for (int _i = 0; _i < 2; ++_i) \
;         __builtin_amdgcn_global_load_lds((const unsigned*)((const char*)(gbase) + (voff)[_i]), (LAS unsigned*)(lds + (bufoff) + ldsw + _i * 8192), 16, 0, 0); } while (0)
; #define PG8_LDA(dst, b, h) do { _Pragma("unroll") for (int m = 0; m < 4; ++m) _Pragma("unroll") for (int k = 0; k < 2; ++k) dst[m][k] = *(const LAS bf16x8*)(lds + PG8_SA(b, h) + aoff + m * 2048 + k * 1024); } while (0)
; #define PG8_LDB(dst, b, h) do { _Pragma("unroll") for (int n = 0; n < 2; ++n) _Pragma("unroll") for (int k = 0; k < 2; ++k) dst[n][k] = *(const LAS bf16x8*)(lds + PG8_SB(b, h) + boff + n * 2048 + k * 1024); } while (0)
; #define PG8_MMA(ai, bj, At, Bt) do { __builtin_amdgcn_s_setprio(1); _Pragma("unroll") for (int m = 0; m < 4; ++m) _Pragma("unroll") for (int n = 0; n < 2; ++n) _Pragma("unroll") for (int k = 0; k < 2; ++k) \
;         acc[ai][bj][m][n] = __builtin_amdgcn_mfma_f32_16x16x32_bf16(Bt[n][k], At[m][k], acc[ai][bj][m][n], 0, 0, 0); __builtin_amdgcn_s_setprio(0); } while (0)
; #define PG8_WAIT_V(n) asm volatile("s_waitcnt vmcnt(" #n ")" ::: "memory")
; #define PG8_WAIT_L(n) asm volatile("s_waitcnt lgkmcnt(" #n ")" ::: "memory")
; #define PG8_BAR __builtin_amdgcn_s_barrier()
; #define PG8_SCHED __builtin_amdgcn_sched_barrier(0)
; template <class Epi, class Sched>
; __device__ __forceinline__ void gemm_phase(LAS unsigned char* lds, const Gemm g, const Sched& S, const Epi& E) {
;     ...
;             PG8_WAIT_V(6); PG8_BAR; PG8_MMA(1, 1, At, B1); PG8_BAR;
;             PG8_LDB(B0, 1, 0); PG8_SCHED; PG8_LDA(At, 1, 0); PG8_STAGE(PG8_SA(0, 1), a2 + hstep, voffA);
;             PG8_WAIT_L(8); PG8_BAR; PG8_WAIT_L(0); PG8_MMA(0, 0, At, B0); PG8_BAR; PG8_SCHED;
;             PG8_LDB(B1, 1, 1); PG8_STAGE(PG8_SB(1, 0), b3, voffB);
;             PG8_BAR; PG8_WAIT_L(0); PG8_MMA(0, 1, At, B1); PG8_BAR;
;             PG8_LDA(At, 1, 1); PG8_STAGE(PG8_SA(1, 0), a3, voffA);
;             PG8_BAR; PG8_WAIT_L(0); PG8_MMA(1, 0, At, B0); PG8_BAR; PG8_SCHED;
.Lgdr643_j:
	s_barrier
	s_setprio 1
	v_mfma_f32_16x16x32_bf16 v[46:49], v[216:219], v[172:175], v[46:49]
	v_mfma_f32_16x16x32_bf16 v[42:45], v[224:227], v[172:175], v[42:45]
	v_mfma_f32_16x16x32_bf16 v[30:33], v[216:219], v[192:195], v[30:33]
	v_mfma_f32_16x16x32_bf16 v[26:29], v[224:227], v[192:195], v[26:29]
	v_mfma_f32_16x16x32_bf16 v[14:17], v[216:219], v[200:203], v[14:17]
	v_mfma_f32_16x16x32_bf16 v[10:13], v[224:227], v[200:203], v[10:13]
	v_mfma_f32_16x16x32_bf16 v[4:7], v[216:219], v[208:211], v[4:7]
	v_mfma_f32_16x16x32_bf16 v[0:3], v[224:227], v[208:211], v[0:3]
	v_mfma_f32_16x16x32_bf16 v[46:49], v[220:223], v[188:191], v[46:49]
	v_mfma_f32_16x16x32_bf16 v[42:45], v[228:231], v[188:191], v[42:45]
	v_mfma_f32_16x16x32_bf16 v[30:33], v[220:223], v[196:199], v[30:33]
	v_mfma_f32_16x16x32_bf16 v[26:29], v[228:231], v[196:199], v[26:29]
	v_mfma_f32_16x16x32_bf16 v[14:17], v[220:223], v[204:207], v[14:17]
	v_mfma_f32_16x16x32_bf16 v[10:13], v[228:231], v[204:207], v[10:13]
	v_mfma_f32_16x16x32_bf16 v[4:7], v[220:223], v[212:215], v[4:7]
	v_mfma_f32_16x16x32_bf16 v[0:3], v[228:231], v[212:215], v[0:3]
	s_setprio 0
	s_add_i32 s21, 16, 0x18000
	v_add_u32_e32 v155, s21, v152
	s_barrier
	ds_read_b128 v[156:159], v155
	ds_read_b128 v[160:163], v155 offset:1024
	ds_read_b128 v[164:167], v155 offset:2048
	ds_read_b128 v[168:171], v155 offset:3072
	s_add_u32 s22, s78, 0x40000
	s_addc_u32 s23, s79, 0
	s_mov_b32 m0, s12
	v_lshl_add_u64 v[216:217], s[22:23], 0, v[146:147]
	ds_read_b128 v[172:175], v154 offset:32768
	ds_read_b128 v[188:191], v154 offset:33792
	ds_read_b128 v[192:195], v154 offset:34816
	ds_read_b128 v[196:199], v154 offset:35840
	ds_read_b128 v[200:203], v154 offset:36864
	ds_read_b128 v[204:207], v154 offset:37888
	ds_read_b128 v[208:211], v154 offset:38912
	ds_read_b128 v[212:215], v154 offset:39936
	global_load_lds_dwordx4 v[216:217], off
	v_lshl_add_u64 v[216:217], s[22:23], 0, v[142:143]
	s_mov_b32 m0, s13
	s_nop 0
	global_load_lds_dwordx4 v[216:217], off
	s_waitcnt lgkmcnt(8)
	s_barrier
	s_waitcnt lgkmcnt(0)
	s_setprio 1
	s_waitcnt lgkmcnt(0)
	v_mfma_f32_16x16x32_bf16 v[126:129], v[156:159], v[172:175], v[126:129]
	v_mfma_f32_16x16x32_bf16 v[122:125], v[164:167], v[172:175], v[122:125]
	v_mfma_f32_16x16x32_bf16 v[118:121], v[156:159], v[192:195], v[118:121]
	v_mfma_f32_16x16x32_bf16 v[114:117], v[164:167], v[192:195], v[114:117]
	v_mfma_f32_16x16x32_bf16 v[102:105], v[156:159], v[200:203], v[102:105]
	v_mfma_f32_16x16x32_bf16 v[98:101], v[164:167], v[200:203], v[98:101]
	v_mfma_f32_16x16x32_bf16 v[86:89], v[156:159], v[208:211], v[86:89]
	v_mfma_f32_16x16x32_bf16 v[82:85], v[164:167], v[208:211], v[82:85]
	v_mfma_f32_16x16x32_bf16 v[126:129], v[160:163], v[188:191], v[126:129]
	v_mfma_f32_16x16x32_bf16 v[122:125], v[168:171], v[188:191], v[122:125]
	v_mfma_f32_16x16x32_bf16 v[118:121], v[160:163], v[196:199], v[118:121]
	v_mfma_f32_16x16x32_bf16 v[114:117], v[168:171], v[196:199], v[114:117]
	v_mfma_f32_16x16x32_bf16 v[102:105], v[160:163], v[204:207], v[102:105]
	v_mfma_f32_16x16x32_bf16 v[98:101], v[168:171], v[204:207], v[98:101]
	v_mfma_f32_16x16x32_bf16 v[86:89], v[160:163], v[212:215], v[86:89]
	v_mfma_f32_16x16x32_bf16 v[82:85], v[168:171], v[212:215], v[82:85]
	s_setprio 0
	s_barrier
	s_add_i32 s78, 16, 0x1c000
	s_add_i32 s21, s21, s9
	v_add_u32_e32 v155, s78, v152
	v_lshl_add_u64 v[232:233], v[232:233], 0, s[94:95]
	s_mov_b32 m0, s21
	ds_read_b128 v[216:219], v155
	ds_read_b128 v[220:223], v155 offset:1024
	ds_read_b128 v[224:227], v155 offset:2048
	ds_read_b128 v[228:231], v155 offset:3072
	global_load_lds_dwordx4 v[232:233], off
	v_lshl_add_u64 v[232:233], v[234:235], 0, s[94:95]
	s_add_i32 m0, s21, 0x2000
	s_nop 0
	global_load_lds_dwordx4 v[232:233], off
	s_barrier
	s_waitcnt lgkmcnt(0)
	s_setprio 1
	s_waitcnt lgkmcnt(0)
	v_mfma_f32_16x16x32_bf16 v[110:113], v[216:219], v[172:175], v[110:113]
	v_mfma_f32_16x16x32_bf16 v[106:109], v[224:227], v[172:175], v[106:109]
	v_mfma_f32_16x16x32_bf16 v[94:97], v[216:219], v[192:195], v[94:97]
	v_mfma_f32_16x16x32_bf16 v[90:93], v[224:227], v[192:195], v[90:93]
	v_mfma_f32_16x16x32_bf16 v[78:81], v[216:219], v[200:203], v[78:81]
	v_mfma_f32_16x16x32_bf16 v[74:77], v[224:227], v[200:203], v[74:77]
	v_mfma_f32_16x16x32_bf16 v[70:73], v[216:219], v[208:211], v[70:73]
	v_mfma_f32_16x16x32_bf16 v[66:69], v[224:227], v[208:211], v[66:69]
	v_mfma_f32_16x16x32_bf16 v[110:113], v[220:223], v[188:191], v[110:113]
	v_mfma_f32_16x16x32_bf16 v[106:109], v[228:231], v[188:191], v[106:109]
	v_mfma_f32_16x16x32_bf16 v[94:97], v[220:223], v[196:199], v[94:97]
	v_mfma_f32_16x16x32_bf16 v[90:93], v[228:231], v[196:199], v[90:93]
	v_mfma_f32_16x16x32_bf16 v[78:81], v[220:223], v[204:207], v[78:81]
	v_mfma_f32_16x16x32_bf16 v[74:77], v[228:231], v[204:207], v[74:77]
	v_mfma_f32_16x16x32_bf16 v[70:73], v[220:223], v[212:215], v[70:73]
	v_mfma_f32_16x16x32_bf16 v[66:69], v[228:231], v[212:215], v[66:69]
	s_setprio 0
	s_mov_b32 m0, s14
	v_lshl_add_u64 v[232:233], v[236:237], 0, s[94:95]
	s_barrier
	ds_read_b128 v[172:175], v154 offset:49152
	ds_read_b128 v[188:191], v154 offset:50176
	ds_read_b128 v[192:195], v154 offset:51200
	ds_read_b128 v[196:199], v154 offset:52224
	ds_read_b128 v[200:203], v154 offset:53248
	ds_read_b128 v[204:207], v154 offset:54272
	ds_read_b128 v[208:211], v154 offset:55296
	ds_read_b128 v[212:215], v154 offset:56320
	global_load_lds_dwordx4 v[232:233], off
	v_lshl_add_u64 v[232:233], v[238:239], 0, s[94:95]
	s_mov_b32 m0, s15
	s_nop 0
	global_load_lds_dwordx4 v[232:233], off
	s_barrier
; #define PG8_STAGE(bufoff, gbase, voff) do { _Pragma("unroll") for (int _i = 0; _i < 2; ++_i) \
;         __builtin_amdgcn_global_load_lds((const unsigned*)((const char*)(gbase) + (voff)[_i]), (LAS unsigned*)(lds + (bufoff) + ldsw + _i * 8192), 16, 0, 0); } while (0)
; #define PG8_MMA(ai, bj, At, Bt) do { __builtin_amdgcn_s_setprio(1); _Pragma("unroll") for (int m = 0; m < 4; ++m) _Pragma("unroll") for (int n = 0; n < 2; ++n) _Pragma("unroll") for (int k = 0; k < 2; ++k) \
;         acc[ai][bj][m][n] = __builtin_amdgcn_mfma_f32_16x16x32_bf16(Bt[n][k], At[m][k], acc[ai][bj][m][n], 0, 0, 0); __builtin_amdgcn_s_setprio(0); } while (0)
; #define PG8_WAIT_V(n) asm volatile("s_waitcnt vmcnt(" #n ")" ::: "memory")
; #define PG8_WAIT_L(n) asm volatile("s_waitcnt lgkmcnt(" #n ")" ::: "memory")
; #define PG8_BAR __builtin_amdgcn_s_barrier()
; #define PG8_SCHED __builtin_amdgcn_sched_barrier(0)
; template <class Epi, class Sched>
; __device__ __forceinline__ void gemm_phase(LAS unsigned char* lds, const Gemm g, const Sched& S, const Epi& E) {
;     ...
;             PG8_BAR; PG8_WAIT_L(0); PG8_MMA(1, 0, At, B0); PG8_BAR; PG8_SCHED;
;             PG8_STAGE(PG8_SB(1, 1), b3 + hstep, voffB);
;             PG8_WAIT_V(6); PG8_BAR; PG8_MMA(1, 1, At, B1); PG8_BAR;
;         }
	s_waitcnt lgkmcnt(0)
	s_setprio 1
	s_waitcnt lgkmcnt(0)
	v_mfma_f32_16x16x32_bf16 v[62:65], v[156:159], v[172:175], v[62:65]
	v_mfma_f32_16x16x32_bf16 v[58:61], v[164:167], v[172:175], v[58:61]
	v_mfma_f32_16x16x32_bf16 v[54:57], v[156:159], v[192:195], v[54:57]
	v_mfma_f32_16x16x32_bf16 v[50:53], v[164:167], v[192:195], v[50:53]
	v_mfma_f32_16x16x32_bf16 v[38:41], v[156:159], v[200:203], v[38:41]
	v_mfma_f32_16x16x32_bf16 v[34:37], v[164:167], v[200:203], v[34:37]
	v_mfma_f32_16x16x32_bf16 v[22:25], v[156:159], v[208:211], v[22:25]
	v_mfma_f32_16x16x32_bf16 v[18:21], v[164:167], v[208:211], v[18:21]
	v_mfma_f32_16x16x32_bf16 v[62:65], v[160:163], v[188:191], v[62:65]
	v_mfma_f32_16x16x32_bf16 v[58:61], v[168:171], v[188:191], v[58:61]
	v_mfma_f32_16x16x32_bf16 v[54:57], v[160:163], v[196:199], v[54:57]
	v_mfma_f32_16x16x32_bf16 v[50:53], v[168:171], v[196:199], v[50:53]
	v_mfma_f32_16x16x32_bf16 v[38:41], v[160:163], v[204:207], v[38:41]
	v_mfma_f32_16x16x32_bf16 v[34:37], v[168:171], v[204:207], v[34:37]
	v_mfma_f32_16x16x32_bf16 v[22:25], v[160:163], v[212:215], v[22:25]
	v_mfma_f32_16x16x32_bf16 v[18:21], v[168:171], v[212:215], v[18:21]
	s_setprio 0
	s_barrier
	s_add_u32 s22, s70, 0x40080
	s_addc_u32 s23, s71, 0
	s_add_i32 s21, s78, s9
	v_lshl_add_u64 v[156:157], s[22:23], 0, v[144:145]
	s_mov_b32 m0, s21
	s_nop 0
	global_load_lds_dwordx4 v[156:157], off
	v_lshl_add_u64 v[156:157], s[22:23], 0, v[140:141]
	s_add_i32 m0, s21, 0x2000
	s_nop 0
	global_load_lds_dwordx4 v[156:157], off
	s_waitcnt vmcnt(6)
	s_barrier
	s_setprio 1
	v_mfma_f32_16x16x32_bf16 v[46:49], v[216:219], v[172:175], v[46:49]
	v_mfma_f32_16x16x32_bf16 v[42:45], v[224:227], v[172:175], v[42:45]
	v_mfma_f32_16x16x32_bf16 v[30:33], v[216:219], v[192:195], v[30:33]
	v_mfma_f32_16x16x32_bf16 v[26:29], v[224:227], v[192:195], v[26:29]
	v_mfma_f32_16x16x32_bf16 v[14:17], v[216:219], v[200:203], v[14:17]
	v_mfma_f32_16x16x32_bf16 v[10:13], v[224:227], v[200:203], v[10:13]
	v_mfma_f32_16x16x32_bf16 v[4:7], v[216:219], v[208:211], v[4:7]
	v_mfma_f32_16x16x32_bf16 v[0:3], v[224:227], v[208:211], v[0:3]
	v_mfma_f32_16x16x32_bf16 v[46:49], v[220:223], v[188:191], v[46:49]
	v_mfma_f32_16x16x32_bf16 v[42:45], v[228:231], v[188:191], v[42:45]
	v_mfma_f32_16x16x32_bf16 v[30:33], v[220:223], v[196:199], v[30:33]
	v_mfma_f32_16x16x32_bf16 v[26:29], v[228:231], v[196:199], v[26:29]
	v_mfma_f32_16x16x32_bf16 v[14:17], v[220:223], v[204:207], v[14:17]
	v_mfma_f32_16x16x32_bf16 v[10:13], v[228:231], v[204:207], v[10:13]
	v_mfma_f32_16x16x32_bf16 v[4:7], v[220:223], v[212:215], v[4:7]
	v_mfma_f32_16x16x32_bf16 v[0:3], v[228:231], v[212:215], v[0:3]
	s_setprio 0
	s_add_i32 s20, s20, 2
	s_add_u32 vcc_lo, vcc_lo, 0x100
	s_addc_u32 vcc_hi, vcc_hi, 0
	s_add_u32 s18, s18, 0x100
	s_addc_u32 s19, s19, 0
	s_cmp_gt_u32 s20, 13
	s_barrier
	s_cbranch_scc0 .LBB0_646
	s_cmp_lg_u64 s[38:39], 0
	s_cbranch_scc1 .Lgdr643_e
	s_add_u32 s100, s66, 0x40080
	s_addc_u32 s101, s67, 0
	v_lshl_add_u64 v[216:217], s[100:101], 0, v[148:149]
	s_add_i32 m0, s11, 0xc000
	s_nop 0
	global_load_lds_dwordx4 v[216:217], off
	v_lshl_add_u64 v[216:217], s[100:101], 0, v[150:151]
	s_add_i32 m0, s11, 0xe000
	s_nop 0
	global_load_lds_dwordx4 v[216:217], off
	s_mov_b32 s98, 1
; __device__ __forceinline__ unsigned pk_bf16(float a, float b) { f32x2 v = {a, b}; bf2_t r = __builtin_convertvector(v, bf2_t); return __builtin_bit_cast(unsigned, r); }
; #define PG8_WAIT_V(n) asm volatile("s_waitcnt vmcnt(" #n ")" ::: "memory")
; #define PG8_BAR __builtin_amdgcn_s_barrier()
;     __device__ __forceinline__ void operator()(const f32x4 (&acc)[2][2][4][2], const Unit& u, int wr, int wc, int fr, int fq) const {
;         const int row0 = u.pm * BM + wr * 64 + fr; int colt = u.pn * BM; bf16_t* base = O;
;         if (split_cols) { const int t = colt / split_cols; base += (size_t)t * split_stride; colt -= t * split_cols; }
;         const int col0 = colt + wc * 32 + 8 * fq;
; #pragma unroll
;         for (int ai = 0; ai < 2; ++ai)
; #pragma unroll
;             for (int m = 0; m < 4; ++m) { const int row = row0 + ai * HALF + m * 16;
;                 bf16_t* rowp = slot_stride ? base + (size_t)(colt >> 7) * slot_stride + (size_t)row * 128 + wc * 32 + 8 * fq : base + (size_t)row * ldc + col0;
; #pragma unroll
;                 for (int bj = 0; bj < 2; ++bj) { const f32x4 v0 = acc[ai][bj][m][0], v1 = acc[ai][bj][m][1];
;                     u32x4 w; w.x = pk_bf16(v0[0], v0[1]); w.y = pk_bf16(v0[2], v0[3]); w.z = pk_bf16(v1[0], v1[1]); w.w = pk_bf16(v1[2], v1[3]);
;                     *(u32x4*)(rowp + (slot_stride ? (size_t)bj * slot_stride : (size_t)bj * HALF)) = w; } }
; template <class Epi, class Sched>
; __device__ __forceinline__ void gemm_phase(LAS unsigned char* lds, const Gemm g, const Sched& S, const Epi& E) {
;     ...
;         E(acc, cur, wr, wc, fr, fq); S.done(cur);
;         if (!has_next) break;
; #pragma unroll
;         for (int a = 0; a < 2; ++a)
; #pragma unroll
;             for (int b = 0; b < 2; ++b)
; #pragma unroll
;                 for (int m = 0; m < 4; ++m)
; #pragma unroll
;                     for (int n = 0; n < 2; ++n) acc[a][b][m][n] = (f32x4){0.f, 0.f, 0.f, 0.f};
;         cur = nxt; cA = nA; cB = nB; ++ui;
;     }
;     PG8_WAIT_V(0);
;     if (wr == 0) PG8_BAR;
;     PG8_BAR;
.Lgdr643_e:
	s_mul_hi_i32 s16, s40, 0x2e8ba2e9
	s_lshr_b32 s17, s16, 31
	s_ashr_i32 s16, s16, 1
	s_add_i32 s19, s16, s17
	s_lshl_b32 s18, s40, 8
	s_mul_i32 s16, s19, 0xbb00000
	s_mul_hi_i32 s17, s19, 0xbb00000
	s_add_u32 s16, s82, s16
	s_mulk_i32 s19, 0xf500
	s_addc_u32 s17, s83, s17
	s_add_i32 s19, s19, s18
	v_or_b32_e32 v156, s19, v153
	v_lshl_add_u32 v155, s42, 8, v9
	v_ashrrev_i32_e32 v157, 31, v156
	v_lshl_add_u64 v[156:157], v[156:157], 1, s[16:17]
	v_cvt_pk_bf16_f32 v70, v70, v71
	v_cvt_pk_bf16_f32 v71, v72, v73
	v_cvt_pk_bf16_f32 v72, v66, v67
	v_add_u32_e32 v66, 0x80, v155
	v_mad_i64_i32 v[158:159], s[16:17], v155, s81, v[156:157]
	v_cvt_pk_bf16_f32 v110, v110, v111
	v_cvt_pk_bf16_f32 v111, v112, v113
	v_cvt_pk_bf16_f32 v112, v106, v107
	v_cvt_pk_bf16_f32 v113, v108, v109
	v_or_b32_e32 v106, 16, v155
	v_mad_i64_i32 v[66:67], s[16:17], v66, s81, v[156:157]
	v_cvt_pk_bf16_f32 v46, v46, v47
	v_cvt_pk_bf16_f32 v47, v48, v49
	v_cvt_pk_bf16_f32 v48, v42, v43
	v_cvt_pk_bf16_f32 v49, v44, v45
	v_add_u32_e32 v42, 0x90, v155
	global_store_dwordx4 v[158:159], v[110:113], off offset:256
	v_cvt_pk_bf16_f32 v94, v94, v95
	v_cvt_pk_bf16_f32 v95, v96, v97
	v_mad_i64_i32 v[110:111], s[16:17], v106, s81, v[156:157]
	v_cvt_pk_bf16_f32 v96, v90, v91
	v_cvt_pk_bf16_f32 v97, v92, v93
	v_or_b32_e32 v90, 32, v155
	global_store_dwordx4 v[66:67], v[46:49], off offset:256
	v_cvt_pk_bf16_f32 v30, v30, v31
	v_cvt_pk_bf16_f32 v31, v32, v33
	v_mad_i64_i32 v[46:47], s[16:17], v42, s81, v[156:157]
	v_cvt_pk_bf16_f32 v32, v26, v27
	v_cvt_pk_bf16_f32 v33, v28, v29
	v_add_u32_e32 v26, 0xa0, v155
	global_store_dwordx4 v[110:111], v[94:97], off offset:256
	v_cvt_pk_bf16_f32 v78, v78, v79
	v_cvt_pk_bf16_f32 v79, v80, v81
	v_mad_i64_i32 v[94:95], s[16:17], v90, s81, v[156:157]
	v_cvt_pk_bf16_f32 v80, v74, v75
	v_cvt_pk_bf16_f32 v81, v76, v77
	v_or_b32_e32 v74, 48, v155
	global_store_dwordx4 v[46:47], v[30:33], off offset:256
	v_cvt_pk_bf16_f32 v14, v14, v15
	v_cvt_pk_bf16_f32 v15, v16, v17
	v_mad_i64_i32 v[30:31], s[16:17], v26, s81, v[156:157]
	v_cvt_pk_bf16_f32 v16, v10, v11
	v_cvt_pk_bf16_f32 v17, v12, v13
	v_add_u32_e32 v10, 0xb0, v155
	v_cvt_pk_bf16_f32 v126, v126, v127
	v_cvt_pk_bf16_f32 v127, v128, v129
	v_cvt_pk_bf16_f32 v128, v122, v123
	v_cvt_pk_bf16_f32 v129, v124, v125
	v_cvt_pk_bf16_f32 v106, v118, v119
	v_cvt_pk_bf16_f32 v107, v120, v121
	v_cvt_pk_bf16_f32 v108, v114, v115
	v_cvt_pk_bf16_f32 v109, v116, v117
	v_cvt_pk_bf16_f32 v90, v102, v103
	v_cvt_pk_bf16_f32 v91, v104, v105
	v_cvt_pk_bf16_f32 v92, v98, v99
	v_cvt_pk_bf16_f32 v93, v100, v101
	global_store_dwordx4 v[94:95], v[78:81], off offset:256
	v_cvt_pk_bf16_f32 v75, v88, v89
	v_cvt_pk_bf16_f32 v76, v82, v83
	v_mad_i64_i32 v[78:79], s[16:17], v74, s81, v[156:157]
	v_cvt_pk_bf16_f32 v74, v86, v87
	v_cvt_pk_bf16_f32 v77, v84, v85
	v_cvt_pk_bf16_f32 v73, v68, v69
	v_cvt_pk_bf16_f32 v62, v62, v63
	v_cvt_pk_bf16_f32 v63, v64, v65
	v_cvt_pk_bf16_f32 v64, v58, v59
	v_cvt_pk_bf16_f32 v65, v60, v61
	v_cvt_pk_bf16_f32 v42, v54, v55
	v_cvt_pk_bf16_f32 v43, v56, v57
	v_cvt_pk_bf16_f32 v44, v50, v51
	v_cvt_pk_bf16_f32 v45, v52, v53
	v_cvt_pk_bf16_f32 v26, v38, v39
	v_cvt_pk_bf16_f32 v27, v40, v41
	v_cvt_pk_bf16_f32 v28, v34, v35
	v_cvt_pk_bf16_f32 v29, v36, v37
	global_store_dwordx4 v[30:31], v[14:17], off offset:256
	v_cvt_pk_bf16_f32 v11, v24, v25
	v_cvt_pk_bf16_f32 v12, v18, v19
	v_mad_i64_i32 v[14:15], s[16:17], v10, s81, v[156:157]
	v_cvt_pk_bf16_f32 v10, v22, v23
	v_cvt_pk_bf16_f32 v13, v20, v21
	v_cvt_pk_bf16_f32 v4, v4, v5
	v_cvt_pk_bf16_f32 v5, v6, v7
	v_cvt_pk_bf16_f32 v6, v0, v1
	v_cvt_pk_bf16_f32 v7, v2, v3
	s_and_b64 vcc, exec, s[38:39]
	s_mov_b32 s40, s72
	s_mov_b32 s42, s74
	s_mov_b64 s[70:71], s[88:89]
	s_mov_b64 s[78:79], s[66:67]
	global_store_dwordx4 v[158:159], v[126:129], off
	global_store_dwordx4 v[110:111], v[106:109], off
	global_store_dwordx4 v[94:95], v[90:93], off
	global_store_dwordx4 v[78:79], v[74:77], off
	global_store_dwordx4 v[78:79], v[70:73], off offset:256
	global_store_dwordx4 v[66:67], v[62:65], off
	global_store_dwordx4 v[46:47], v[42:45], off
	global_store_dwordx4 v[30:31], v[26:29], off
	global_store_dwordx4 v[14:15], v[10:13], off
	global_store_dwordx4 v[14:15], v[4:7], off offset:256
	s_cbranch_vccz .LBB0_643
	s_waitcnt vmcnt(0)
	s_cmpk_gt_u32 s6, 0xff
	s_cbranch_scc1 .LBB0_650
	s_barrier

; #define PG8_STAGE(bufoff, gbase, voff) do { _Pragma("unroll") for (int _i = 0; _i < 2; ++_i) \
;         __builtin_amdgcn_global_load_lds((const unsigned*)((const char*)(gbase) + (voff)[_i]), (LAS unsigned*)(lds + (bufoff) + ldsw + _i * 8192), 16, 0, 0); } while (0)
; #define PG8_WAIT_V(n) asm volatile("s_waitcnt vmcnt(" #n ")" ::: "memory")
; #define PG8_BAR __builtin_amdgcn_s_barrier()
; template <class Epi, class Sched>
; __device__ __forceinline__ void gemm_phase(LAS unsigned char* lds, const Gemm g, const Sched& S, const Epi& E) {
;     ...
;     for (int i = 0; i < 2; ++i) { int R, C; stage_rc(tid * 16 + i * 8192, R, C); const int Rb = Epi::PERM ? ((R & ~31) + perm32(R & 31)) : R;
;         voffA[i] = (unsigned)(R * K + C) * 2u; voffB[i] = (unsigned)(Rb * K + C) * 2u; }
;     const size_t kstep = (size_t)(BK * 2);
;     const size_t hstep = (size_t)HALF * K * 2;
;     const size_t tstep = 2 * hstep;
;     const unsigned ldsw = (unsigned)wid * 1024u;
;     const int aoff = lds_byte(wr * 64 + fr, fq * 8), boff = lds_byte(wc * 32 + fr, fq * 8);
;     ...
;     Unit cur, nxt; int ui = 0;
;     if (!S.next(0, cur)) return;
;     f32x4 acc[2][2][4][2];
; #pragma unroll
;     for (int a = 0; a < 2; ++a)
; #pragma unroll
;         for (int b = 0; b < 2; ++b)
; #pragma unroll
;             for (int m = 0; m < 4; ++m)
; #pragma unroll
;                 for (int n = 0; n < 2; ++n) acc[a][b][m][n] = (f32x4){0.f, 0.f, 0.f, 0.f};
;     bf16x8 At[4][2], B0[2][2], B1[2][2];
;     const char* cA = (const char*)g.A + (size_t)cur.pm * tstep; const char* cB = (const char*)g.Bt + (size_t)cur.pn * tstep;
;     S.a_ready(cur);
;     PG8_STAGE(PG8_SB(0, 0), cB, voffB); PG8_STAGE(PG8_SA(0, 0), cA, voffA); PG8_STAGE(PG8_SB(0, 1), cB + hstep, voffB); PG8_STAGE(PG8_SA(0, 1), cA + hstep, voffA);
;     if (wr == 1) PG8_BAR;
;     PG8_WAIT_V(4); PG8_BAR;
;     PG8_STAGE(PG8_SB(1, 0), cB + kstep, voffB); PG8_STAGE(PG8_SA(1, 0), cA + kstep, voffA); PG8_STAGE(PG8_SB(1, 1), cB + hstep + kstep, voffB);
;     PG8_WAIT_V(6); PG8_BAR;
.LBB0_817:
	v_lshrrev_b32_e32 v20, 1, v18
	v_and_b32_e32 v20, 24, v20
	s_lshl_b32 s0, s0, 5
	v_and_b32_e32 v19, 15, v18
	v_lshlrev_b32_e32 v21, 1, v20
	v_lshlrev_b32_e32 v18, 2, v18
	s_and_b32 s16, s0, 0x60
	s_add_i32 m0, s11, 0x18000
	v_lshl_add_u64 v[6:7], v[6:7], 0, s[94:95]
	v_lshl_or_b32 v9, s1, 6, v19
	v_lshl_or_b32 v19, v19, 6, v21
	s_lshl_b32 s1, s1, 13
	v_and_b32_e32 v18, 32, v18
	s_lshl_b32 s0, s16, 7
	s_waitcnt vmcnt(4)
	s_barrier
	global_load_lds_dwordx4 v[6:7], off
	v_lshl_add_u64 v[4:5], v[4:5], 0, s[94:95]
	s_add_i32 m0, s11, 0x1a000
	s_add_i32 s14, s11, 0x8000
	s_add_i32 s15, s11, 0xa000
	v_bitop3_b32 v152, v19, s0, v18 bitop3:0xde
	global_load_lds_dwordx4 v[4:5], off
	v_lshl_add_u64 v[2:3], v[2:3], 0, s[94:95]
	s_mov_b32 m0, s14
	s_add_u32 s0, s72, 0xb0080
	v_bitop3_b32 v21, v19, s1, v18 bitop3:0xde
	global_load_lds_dwordx4 v[2:3], off
	v_lshl_add_u64 v[0:1], v[0:1], 0, s[94:95]
	s_mov_b32 m0, s15
	s_addc_u32 s1, s73, 0
	global_load_lds_dwordx4 v[0:1], off
	s_add_i32 m0, s11, 0x1c000
	v_lshl_add_u64 v[0:1], s[0:1], 0, v[144:145]
	global_load_lds_dwordx4 v[0:1], off
	v_lshl_add_u64 v[0:1], s[0:1], 0, v[140:141]
	s_add_i32 m0, s11, 0x1e000
	v_or_b32_e32 v153, s16, v20
	global_load_lds_dwordx4 v[0:1], off
	v_lshrrev_b32_e32 v1, 1, v15
	v_mul_lo_u32 v0, v14, s20
	s_mov_b32 s16, 0xb000
	v_mad_u64_u32 v[0:1], s[0:1], v1, s16, v[0:1]
	v_or_b32_e32 v0, v0, v16
	v_add_lshl_u32 v0, v0, v17, 1
	v_mov_b32_e32 v1, v8
	s_mov_b64 s[18:19], 0xb0080
	v_lshl_add_u64 v[148:149], v[0:1], 0, s[18:19]
	v_lshrrev_b32_e32 v1, 1, v10
	v_mul_lo_u32 v0, v11, s20
	v_mad_u64_u32 v[0:1], s[0:1], v1, s16, v[0:1]
	s_waitcnt vmcnt(6)
	v_or_b32_e32 v0, v0, v12
	v_add_lshl_u32 v0, v0, v13, 1
	v_mov_b32_e32 v1, v8
	v_lshl_add_u64 v[150:151], v[0:1], 0, s[18:19]
	s_mov_b32 s79, 0
	v_add_u32_e32 v154, 16, v21
	s_barrier
	s_mov_b32 s98, 0

; #define PG8_STAGE(bufoff, gbase, voff) do { _Pragma("unroll") for (int _i = 0; _i < 2; ++_i) \
;         __builtin_amdgcn_global_load_lds((const unsigned*)((const char*)(gbase) + (voff)[_i]), (LAS unsigned*)(lds + (bufoff) + ldsw + _i * 8192), 16, 0, 0); } while (0)
; #define PG8_LDA(dst, b, h) do { _Pragma("unroll") for (int m = 0; m < 4; ++m) _Pragma("unroll") for (int k = 0; k < 2; ++k) dst[m][k] = *(const LAS bf16x8*)(lds + PG8_SA(b, h) + aoff + m * 2048 + k * 1024); } while (0)
; #define PG8_LDB(dst, b, h) do { _Pragma("unroll") for (int n = 0; n < 2; ++n) _Pragma("unroll") for (int k = 0; k < 2; ++k) dst[n][k] = *(const LAS bf16x8*)(lds + PG8_SB(b, h) + boff + n * 2048 + k * 1024); } while (0)
; #define PG8_MMA(ai, bj, At, Bt) do { __builtin_amdgcn_s_setprio(1); _Pragma("unroll") for (int m = 0; m < 4; ++m) _Pragma("unroll") for (int n = 0; n < 2; ++n) _Pragma("unroll") for (int k = 0; k < 2; ++k) \
;         acc[ai][bj][m][n] = __builtin_amdgcn_mfma_f32_16x16x32_bf16(Bt[n][k], At[m][k], acc[ai][bj][m][n], 0, 0, 0); __builtin_amdgcn_s_setprio(0); } while (0)
; #define PG8_WAIT_L(n) asm volatile("s_waitcnt lgkmcnt(" #n ")" ::: "memory")
; #define PG8_BAR __builtin_amdgcn_s_barrier()
; #define PG8_SCHED __builtin_amdgcn_sched_barrier(0)
; template <class Epi, class Sched>
; __device__ __forceinline__ void gemm_phase(LAS unsigned char* lds, const Gemm g, const Sched& S, const Epi& E) {
;     ...
;         for (int t = 0; t < nt; t += 2) {
;             const bool last = (t == nt - 2);
;             const char* a1 = cA + (size_t)(t + 1) * kstep;
;             const char* a2 = last ? nA : cA + (size_t)(t + 2) * kstep; const char* b2 = last ? nB : cB + (size_t)(t + 2) * kstep;
;             const char* a3 = a2 + kstep; const char* b3 = b2 + kstep;
;             if (last && has_next) S.a_ready(nxt);
;             PG8_LDB(B0, 0, 0); PG8_SCHED; PG8_LDA(At, 0, 0); PG8_STAGE(PG8_SA(1, 1), a1 + hstep, voffA);
;             PG8_WAIT_L(8); PG8_BAR; PG8_WAIT_L(0); PG8_MMA(0, 0, At, B0); PG8_BAR; PG8_SCHED;
;             PG8_LDB(B1, 0, 1); PG8_STAGE(PG8_SB(0, 0), b2, voffB);
;             PG8_BAR; PG8_WAIT_L(0); PG8_MMA(0, 1, At, B1); PG8_BAR;
;             PG8_LDA(At, 0, 1); PG8_STAGE(PG8_SA(0, 0), a2, voffA);
;             PG8_BAR; PG8_WAIT_L(0); PG8_MMA(1, 0, At, B0); PG8_BAR; PG8_SCHED;
;             PG8_STAGE(PG8_SB(0, 1), b2 + hstep, voffB);
.LBB0_825:
	s_add_u32 s72, s42, 0x100
	s_addc_u32 s73, s43, 0
	s_add_i32 s19, 16, 0x10000
	v_add_u32_e32 v155, s19, v152
	ds_read_b128 v[156:159], v155
	ds_read_b128 v[160:163], v155 offset:1024
	ds_read_b128 v[164:167], v155 offset:2048
	ds_read_b128 v[168:171], v155 offset:3072
	s_cmp_eq_u32 s18, 40
	s_cselect_b32 s71, s41, s73
	s_cselect_b32 s70, s40, s72
	s_cselect_b32 s67, s1, s17
	s_cselect_b32 s66, s0, s16
	v_lshl_add_u64 v[216:217], s[42:43], 0, v[148:149]
	s_add_i32 m0, s11, 0xc000
	ds_read_b128 v[172:175], v154
	ds_read_b128 v[188:191], v154 offset:1024
	ds_read_b128 v[192:195], v154 offset:2048
	ds_read_b128 v[196:199], v154 offset:3072
	ds_read_b128 v[200:203], v154 offset:4096
	ds_read_b128 v[204:207], v154 offset:5120
	ds_read_b128 v[208:211], v154 offset:6144
	ds_read_b128 v[212:215], v154 offset:7168
	global_load_lds_dwordx4 v[216:217], off
	v_lshl_add_u64 v[216:217], s[42:43], 0, v[150:151]
	s_add_i32 m0, s11, 0xe000
	s_nop 0
	global_load_lds_dwordx4 v[216:217], off
	s_waitcnt lgkmcnt(8)
	s_barrier
	s_waitcnt lgkmcnt(0)
	s_setprio 1
	s_waitcnt lgkmcnt(0)
	v_mfma_f32_16x16x32_bf16 v[126:129], v[156:159], v[172:175], v[126:129]
	v_mfma_f32_16x16x32_bf16 v[122:125], v[164:167], v[172:175], v[122:125]
	v_mfma_f32_16x16x32_bf16 v[118:121], v[156:159], v[192:195], v[118:121]
	v_mfma_f32_16x16x32_bf16 v[114:117], v[164:167], v[192:195], v[114:117]
	v_mfma_f32_16x16x32_bf16 v[102:105], v[156:159], v[200:203], v[102:105]
	v_mfma_f32_16x16x32_bf16 v[98:101], v[164:167], v[200:203], v[98:101]
	v_mfma_f32_16x16x32_bf16 v[86:89], v[156:159], v[208:211], v[86:89]
	v_mfma_f32_16x16x32_bf16 v[82:85], v[164:167], v[208:211], v[82:85]
	v_mfma_f32_16x16x32_bf16 v[126:129], v[160:163], v[188:191], v[126:129]
	v_mfma_f32_16x16x32_bf16 v[122:125], v[168:171], v[188:191], v[122:125]
	v_mfma_f32_16x16x32_bf16 v[118:121], v[160:163], v[196:199], v[118:121]
	v_mfma_f32_16x16x32_bf16 v[114:117], v[168:171], v[196:199], v[114:117]
	v_mfma_f32_16x16x32_bf16 v[102:105], v[160:163], v[204:207], v[102:105]
	v_mfma_f32_16x16x32_bf16 v[98:101], v[168:171], v[204:207], v[98:101]
	v_mfma_f32_16x16x32_bf16 v[86:89], v[160:163], v[212:215], v[86:89]
	v_mfma_f32_16x16x32_bf16 v[82:85], v[168:171], v[212:215], v[82:85]
	s_setprio 0
	s_barrier
	s_add_i32 s22, 16, 0x14000
	s_add_i32 s19, s19, s9
	v_add_u32_e32 v155, s22, v152
	v_lshl_add_u64 v[232:233], s[66:67], 0, v[144:145]
	s_mov_b32 m0, s19
	ds_read_b128 v[216:219], v155
	ds_read_b128 v[220:223], v155 offset:1024
	ds_read_b128 v[224:227], v155 offset:2048
	ds_read_b128 v[228:231], v155 offset:3072
	global_load_lds_dwordx4 v[232:233], off
	v_lshl_add_u64 v[234:235], s[66:67], 0, v[140:141]
	s_add_i32 m0, s19, 0x2000
	s_nop 0
	global_load_lds_dwordx4 v[234:235], off
	s_barrier
	s_waitcnt lgkmcnt(0)
	s_setprio 1
	s_waitcnt lgkmcnt(0)
	v_mfma_f32_16x16x32_bf16 v[110:113], v[216:219], v[172:175], v[110:113]
	v_mfma_f32_16x16x32_bf16 v[106:109], v[224:227], v[172:175], v[106:109]
	v_mfma_f32_16x16x32_bf16 v[94:97], v[216:219], v[192:195], v[94:97]
	v_mfma_f32_16x16x32_bf16 v[90:93], v[224:227], v[192:195], v[90:93]
	v_mfma_f32_16x16x32_bf16 v[78:81], v[216:219], v[200:203], v[78:81]
	v_mfma_f32_16x16x32_bf16 v[74:77], v[224:227], v[200:203], v[74:77]
	v_mfma_f32_16x16x32_bf16 v[70:73], v[216:219], v[208:211], v[70:73]
	v_mfma_f32_16x16x32_bf16 v[66:69], v[224:227], v[208:211], v[66:69]
	v_mfma_f32_16x16x32_bf16 v[110:113], v[220:223], v[188:191], v[110:113]
	v_mfma_f32_16x16x32_bf16 v[106:109], v[228:231], v[188:191], v[106:109]
	v_mfma_f32_16x16x32_bf16 v[94:97], v[220:223], v[196:199], v[94:97]
	v_mfma_f32_16x16x32_bf16 v[90:93], v[228:231], v[196:199], v[90:93]
	v_mfma_f32_16x16x32_bf16 v[78:81], v[220:223], v[204:207], v[78:81]
	v_mfma_f32_16x16x32_bf16 v[74:77], v[228:231], v[204:207], v[74:77]
	v_mfma_f32_16x16x32_bf16 v[70:73], v[220:223], v[212:215], v[70:73]
	v_mfma_f32_16x16x32_bf16 v[66:69], v[228:231], v[212:215], v[66:69]
	s_setprio 0
	s_mov_b32 m0, s11
	v_lshl_add_u64 v[236:237], s[70:71], 0, v[146:147]
	s_barrier
	ds_read_b128 v[172:175], v154 offset:16384
	ds_read_b128 v[188:191], v154 offset:17408
	ds_read_b128 v[192:195], v154 offset:18432
	ds_read_b128 v[196:199], v154 offset:19456
	ds_read_b128 v[200:203], v154 offset:20480
	ds_read_b128 v[204:207], v154 offset:21504
	ds_read_b128 v[208:211], v154 offset:22528
	ds_read_b128 v[212:215], v154 offset:23552
	global_load_lds_dwordx4 v[236:237], off
	v_lshl_add_u64 v[238:239], s[70:71], 0, v[142:143]
	s_mov_b32 m0, s74
	s_nop 0
	global_load_lds_dwordx4 v[238:239], off
	s_barrier
	s_waitcnt lgkmcnt(0)
	s_setprio 1
	s_waitcnt lgkmcnt(0)
	v_mfma_f32_16x16x32_bf16 v[62:65], v[156:159], v[172:175], v[62:65]
	v_mfma_f32_16x16x32_bf16 v[58:61], v[164:167], v[172:175], v[58:61]
	v_mfma_f32_16x16x32_bf16 v[54:57], v[156:159], v[192:195], v[54:57]
	v_mfma_f32_16x16x32_bf16 v[50:53], v[164:167], v[192:195], v[50:53]
	v_mfma_f32_16x16x32_bf16 v[38:41], v[156:159], v[200:203], v[38:41]
	v_mfma_f32_16x16x32_bf16 v[34:37], v[164:167], v[200:203], v[34:37]
	v_mfma_f32_16x16x32_bf16 v[22:25], v[156:159], v[208:211], v[22:25]
	v_mfma_f32_16x16x32_bf16 v[18:21], v[164:167], v[208:211], v[18:21]
	v_mfma_f32_16x16x32_bf16 v[62:65], v[160:163], v[188:191], v[62:65]
	v_mfma_f32_16x16x32_bf16 v[58:61], v[168:171], v[188:191], v[58:61]
	v_mfma_f32_16x16x32_bf16 v[54:57], v[160:163], v[196:199], v[54:57]
	v_mfma_f32_16x16x32_bf16 v[50:53], v[168:171], v[196:199], v[50:53]
	v_mfma_f32_16x16x32_bf16 v[38:41], v[160:163], v[204:207], v[38:41]
	v_mfma_f32_16x16x32_bf16 v[34:37], v[168:171], v[204:207], v[34:37]
	v_mfma_f32_16x16x32_bf16 v[22:25], v[160:163], v[212:215], v[22:25]
	v_mfma_f32_16x16x32_bf16 v[18:21], v[168:171], v[212:215], v[18:21]
	s_setprio 0
	s_barrier
	s_add_u32 s20, s66, 0xb0000
	s_addc_u32 s21, s67, 0
	s_add_i32 s19, s22, s9
	v_lshl_add_u64 v[156:157], s[20:21], 0, v[144:145]
	s_mov_b32 m0, s19
	s_nop 0
	global_load_lds_dwordx4 v[156:157], off
	v_lshl_add_u64 v[156:157], s[20:21], 0, v[140:141]
	s_add_i32 m0, s19, 0x2000
	s_nop 0
	global_load_lds_dwordx4 v[156:157], off
	s_cmp_eq_u32 s98, 0
	s_cbranch_scc1 .Lgdr818_n
	s_waitcnt vmcnt(24)
	s_mov_b32 s98, 0
	s_branch .Lgdr818_j

; #define PG8_STAGE(bufoff, gbase, voff) do { _Pragma("unroll") for (int _i = 0; _i < 2; ++_i) \
;         __builtin_amdgcn_global_load_lds((const unsigned*)((const char*)(gbase) + (voff)[_i]), (LAS unsigned*)(lds + (bufoff) + ldsw + _i * 8192), 16, 0, 0); } while (0)
; #define PG8_LDA(dst, b, h) do { _Pragma("unroll") for (int m = 0; m < 4; ++m) _Pragma("unroll") for (int k = 0; k < 2; ++k) dst[m][k] = *(const LAS bf16x8*)(lds + PG8_SA(b, h) + aoff + m * 2048 + k * 1024); } while (0)
; #define PG8_LDB(dst, b, h) do { _Pragma("unroll") for (int n = 0; n < 2; ++n) _Pragma("unroll") for (int k = 0; k < 2; ++k) dst[n][k] = *(const LAS bf16x8*)(lds + PG8_SB(b, h) + boff + n * 2048 + k * 1024); } while (0)
; #define PG8_MMA(ai, bj, At, Bt) do { __builtin_amdgcn_s_setprio(1); _Pragma("unroll") for (int m = 0; m < 4; ++m) _Pragma("unroll") for (int n = 0; n < 2; ++n) _Pragma("unroll") for (int k = 0; k < 2; ++k) \
;         acc[ai][bj][m][n] = __builtin_amdgcn_mfma_f32_16x16x32_bf16(Bt[n][k], At[m][k], acc[ai][bj][m][n], 0, 0, 0); __builtin_amdgcn_s_setprio(0); } while (0)
; #define PG8_WAIT_V(n) asm volatile("s_waitcnt vmcnt(" #n ")" ::: "memory")
; #define PG8_WAIT_L(n) asm volatile("s_waitcnt lgkmcnt(" #n ")" ::: "memory")
; #define PG8_BAR __builtin_amdgcn_s_barrier()
; #define PG8_SCHED __builtin_amdgcn_sched_barrier(0)
; template <class Epi, class Sched>
; __device__ __forceinline__ void gemm_phase(LAS unsigned char* lds, const Gemm g, const Sched& S, const Epi& E) {
;     ...
;             PG8_WAIT_V(6); PG8_BAR; PG8_MMA(1, 1, At, B1); PG8_BAR;
;             PG8_LDB(B0, 1, 0); PG8_SCHED; PG8_LDA(At, 1, 0); PG8_STAGE(PG8_SA(0, 1), a2 + hstep, voffA);
;             PG8_WAIT_L(8); PG8_BAR; PG8_WAIT_L(0); PG8_MMA(0, 0, At, B0); PG8_BAR; PG8_SCHED;
;             PG8_LDB(B1, 1, 1); PG8_STAGE(PG8_SB(1, 0), b3, voffB);
;             PG8_BAR; PG8_WAIT_L(0); PG8_MMA(0, 1, At, B1); PG8_BAR;
;             PG8_LDA(At, 1, 1); PG8_STAGE(PG8_SA(1, 0), a3, voffA);
;             PG8_BAR; PG8_WAIT_L(0); PG8_MMA(1, 0, At, B0); PG8_BAR; PG8_SCHED;
.Lgdr818_j:
	s_barrier
	s_setprio 1
	v_mfma_f32_16x16x32_bf16 v[46:49], v[216:219], v[172:175], v[46:49]
	v_mfma_f32_16x16x32_bf16 v[42:45], v[224:227], v[172:175], v[42:45]
	v_mfma_f32_16x16x32_bf16 v[30:33], v[216:219], v[192:195], v[30:33]
	v_mfma_f32_16x16x32_bf16 v[26:29], v[224:227], v[192:195], v[26:29]
	v_mfma_f32_16x16x32_bf16 v[14:17], v[216:219], v[200:203], v[14:17]
	v_mfma_f32_16x16x32_bf16 v[10:13], v[224:227], v[200:203], v[10:13]
	v_mfma_f32_16x16x32_bf16 v[4:7], v[216:219], v[208:211], v[4:7]
	v_mfma_f32_16x16x32_bf16 v[0:3], v[224:227], v[208:211], v[0:3]
	v_mfma_f32_16x16x32_bf16 v[46:49], v[220:223], v[188:191], v[46:49]
	v_mfma_f32_16x16x32_bf16 v[42:45], v[228:231], v[188:191], v[42:45]
	v_mfma_f32_16x16x32_bf16 v[30:33], v[220:223], v[196:199], v[30:33]
	v_mfma_f32_16x16x32_bf16 v[26:29], v[228:231], v[196:199], v[26:29]
	v_mfma_f32_16x16x32_bf16 v[14:17], v[220:223], v[204:207], v[14:17]
	v_mfma_f32_16x16x32_bf16 v[10:13], v[228:231], v[204:207], v[10:13]
	v_mfma_f32_16x16x32_bf16 v[4:7], v[220:223], v[212:215], v[4:7]
	v_mfma_f32_16x16x32_bf16 v[0:3], v[228:231], v[212:215], v[0:3]
	s_setprio 0
	s_add_i32 s19, 16, 0x18000
	v_add_u32_e32 v155, s19, v152
	s_barrier
	ds_read_b128 v[156:159], v155
	ds_read_b128 v[160:163], v155 offset:1024
	ds_read_b128 v[164:167], v155 offset:2048
	ds_read_b128 v[168:171], v155 offset:3072
	s_add_u32 s20, s70, 0xb0000
	s_addc_u32 s21, s71, 0
	s_mov_b32 m0, s12
	v_lshl_add_u64 v[216:217], s[20:21], 0, v[146:147]
	ds_read_b128 v[172:175], v154 offset:32768
	ds_read_b128 v[188:191], v154 offset:33792
	ds_read_b128 v[192:195], v154 offset:34816
	ds_read_b128 v[196:199], v154 offset:35840
	ds_read_b128 v[200:203], v154 offset:36864
	ds_read_b128 v[204:207], v154 offset:37888
	ds_read_b128 v[208:211], v154 offset:38912
	ds_read_b128 v[212:215], v154 offset:39936
	global_load_lds_dwordx4 v[216:217], off
	v_lshl_add_u64 v[216:217], s[20:21], 0, v[142:143]
	s_mov_b32 m0, s13
	s_nop 0
	global_load_lds_dwordx4 v[216:217], off
	s_waitcnt lgkmcnt(8)
	s_barrier
	s_waitcnt lgkmcnt(0)
	s_setprio 1
	s_waitcnt lgkmcnt(0)
	v_mfma_f32_16x16x32_bf16 v[126:129], v[156:159], v[172:175], v[126:129]
	v_mfma_f32_16x16x32_bf16 v[122:125], v[164:167], v[172:175], v[122:125]
	v_mfma_f32_16x16x32_bf16 v[118:121], v[156:159], v[192:195], v[118:121]
	v_mfma_f32_16x16x32_bf16 v[114:117], v[164:167], v[192:195], v[114:117]
	v_mfma_f32_16x16x32_bf16 v[102:105], v[156:159], v[200:203], v[102:105]
	v_mfma_f32_16x16x32_bf16 v[98:101], v[164:167], v[200:203], v[98:101]
	v_mfma_f32_16x16x32_bf16 v[86:89], v[156:159], v[208:211], v[86:89]
	v_mfma_f32_16x16x32_bf16 v[82:85], v[164:167], v[208:211], v[82:85]
	v_mfma_f32_16x16x32_bf16 v[126:129], v[160:163], v[188:191], v[126:129]
	v_mfma_f32_16x16x32_bf16 v[122:125], v[168:171], v[188:191], v[122:125]
	v_mfma_f32_16x16x32_bf16 v[118:121], v[160:163], v[196:199], v[118:121]
	v_mfma_f32_16x16x32_bf16 v[114:117], v[168:171], v[196:199], v[114:117]
	v_mfma_f32_16x16x32_bf16 v[102:105], v[160:163], v[204:207], v[102:105]
	v_mfma_f32_16x16x32_bf16 v[98:101], v[168:171], v[204:207], v[98:101]
	v_mfma_f32_16x16x32_bf16 v[86:89], v[160:163], v[212:215], v[86:89]
	v_mfma_f32_16x16x32_bf16 v[82:85], v[168:171], v[212:215], v[82:85]
	s_setprio 0
	s_barrier
	s_add_i32 s22, 16, 0x1c000
	s_add_i32 s19, s19, s9
	v_add_u32_e32 v155, s22, v152
	v_lshl_add_u64 v[232:233], v[232:233], 0, s[94:95]
	s_mov_b32 m0, s19
	ds_read_b128 v[216:219], v155
	ds_read_b128 v[220:223], v155 offset:1024
	ds_read_b128 v[224:227], v155 offset:2048
	ds_read_b128 v[228:231], v155 offset:3072
	global_load_lds_dwordx4 v[232:233], off
	v_lshl_add_u64 v[232:233], v[234:235], 0, s[94:95]
	s_add_i32 m0, s19, 0x2000
	s_nop 0
	global_load_lds_dwordx4 v[232:233], off
	s_barrier
	s_waitcnt lgkmcnt(0)
	s_setprio 1
	s_waitcnt lgkmcnt(0)
	v_mfma_f32_16x16x32_bf16 v[110:113], v[216:219], v[172:175], v[110:113]
	v_mfma_f32_16x16x32_bf16 v[106:109], v[224:227], v[172:175], v[106:109]
	v_mfma_f32_16x16x32_bf16 v[94:97], v[216:219], v[192:195], v[94:97]
	v_mfma_f32_16x16x32_bf16 v[90:93], v[224:227], v[192:195], v[90:93]
	v_mfma_f32_16x16x32_bf16 v[78:81], v[216:219], v[200:203], v[78:81]
	v_mfma_f32_16x16x32_bf16 v[74:77], v[224:227], v[200:203], v[74:77]
	v_mfma_f32_16x16x32_bf16 v[70:73], v[216:219], v[208:211], v[70:73]
	v_mfma_f32_16x16x32_bf16 v[66:69], v[224:227], v[208:211], v[66:69]
	v_mfma_f32_16x16x32_bf16 v[110:113], v[220:223], v[188:191], v[110:113]
	v_mfma_f32_16x16x32_bf16 v[106:109], v[228:231], v[188:191], v[106:109]
	v_mfma_f32_16x16x32_bf16 v[94:97], v[220:223], v[196:199], v[94:97]
	v_mfma_f32_16x16x32_bf16 v[90:93], v[228:231], v[196:199], v[90:93]
	v_mfma_f32_16x16x32_bf16 v[78:81], v[220:223], v[204:207], v[78:81]
	v_mfma_f32_16x16x32_bf16 v[74:77], v[228:231], v[204:207], v[74:77]
	v_mfma_f32_16x16x32_bf16 v[70:73], v[220:223], v[212:215], v[70:73]
	v_mfma_f32_16x16x32_bf16 v[66:69], v[228:231], v[212:215], v[66:69]
	s_setprio 0
	s_mov_b32 m0, s14
	v_lshl_add_u64 v[232:233], v[236:237], 0, s[94:95]
	s_barrier
	ds_read_b128 v[172:175], v154 offset:49152
	ds_read_b128 v[188:191], v154 offset:50176
	ds_read_b128 v[192:195], v154 offset:51200
	ds_read_b128 v[196:199], v154 offset:52224
	ds_read_b128 v[200:203], v154 offset:53248
	ds_read_b128 v[204:207], v154 offset:54272
	ds_read_b128 v[208:211], v154 offset:55296
	ds_read_b128 v[212:215], v154 offset:56320
	global_load_lds_dwordx4 v[232:233], off
	v_lshl_add_u64 v[232:233], v[238:239], 0, s[94:95]
	s_mov_b32 m0, s15
	s_nop 0
	global_load_lds_dwordx4 v[232:233], off
	s_barrier
; #define PG8_STAGE(bufoff, gbase, voff) do { _Pragma("unroll") for (int _i = 0; _i < 2; ++_i) \
;         __builtin_amdgcn_global_load_lds((const unsigned*)((const char*)(gbase) + (voff)[_i]), (LAS unsigned*)(lds + (bufoff) + ldsw + _i * 8192), 16, 0, 0); } while (0)
; #define PG8_MMA(ai, bj, At, Bt) do { __builtin_amdgcn_s_setprio(1); _Pragma("unroll") for (int m = 0; m < 4; ++m) _Pragma("unroll") for (int n = 0; n < 2; ++n) _Pragma("unroll") for (int k = 0; k < 2; ++k) \
;         acc[ai][bj][m][n] = __builtin_amdgcn_mfma_f32_16x16x32_bf16(Bt[n][k], At[m][k], acc[ai][bj][m][n], 0, 0, 0); __builtin_amdgcn_s_setprio(0); } while (0)
; #define PG8_WAIT_V(n) asm volatile("s_waitcnt vmcnt(" #n ")" ::: "memory")
; #define PG8_WAIT_L(n) asm volatile("s_waitcnt lgkmcnt(" #n ")" ::: "memory")
; #define PG8_BAR __builtin_amdgcn_s_barrier()
; #define PG8_SCHED __builtin_amdgcn_sched_barrier(0)
; template <class Epi, class Sched>
; __device__ __forceinline__ void gemm_phase(LAS unsigned char* lds, const Gemm g, const Sched& S, const Epi& E) {
;     ...
;             PG8_BAR; PG8_WAIT_L(0); PG8_MMA(1, 0, At, B0); PG8_BAR; PG8_SCHED;
;             PG8_STAGE(PG8_SB(1, 1), b3 + hstep, voffB);
;             PG8_WAIT_V(6); PG8_BAR; PG8_MMA(1, 1, At, B1); PG8_BAR;
;         }
	s_waitcnt lgkmcnt(0)
	s_setprio 1
	s_waitcnt lgkmcnt(0)
	v_mfma_f32_16x16x32_bf16 v[62:65], v[156:159], v[172:175], v[62:65]
	v_mfma_f32_16x16x32_bf16 v[58:61], v[164:167], v[172:175], v[58:61]
	v_mfma_f32_16x16x32_bf16 v[54:57], v[156:159], v[192:195], v[54:57]
	v_mfma_f32_16x16x32_bf16 v[50:53], v[164:167], v[192:195], v[50:53]
	v_mfma_f32_16x16x32_bf16 v[38:41], v[156:159], v[200:203], v[38:41]
	v_mfma_f32_16x16x32_bf16 v[34:37], v[164:167], v[200:203], v[34:37]
	v_mfma_f32_16x16x32_bf16 v[22:25], v[156:159], v[208:211], v[22:25]
	v_mfma_f32_16x16x32_bf16 v[18:21], v[164:167], v[208:211], v[18:21]
	v_mfma_f32_16x16x32_bf16 v[62:65], v[160:163], v[188:191], v[62:65]
	v_mfma_f32_16x16x32_bf16 v[58:61], v[168:171], v[188:191], v[58:61]
	v_mfma_f32_16x16x32_bf16 v[54:57], v[160:163], v[196:199], v[54:57]
	v_mfma_f32_16x16x32_bf16 v[50:53], v[168:171], v[196:199], v[50:53]
	v_mfma_f32_16x16x32_bf16 v[38:41], v[160:163], v[204:207], v[38:41]
	v_mfma_f32_16x16x32_bf16 v[34:37], v[168:171], v[204:207], v[34:37]
	v_mfma_f32_16x16x32_bf16 v[22:25], v[160:163], v[212:215], v[22:25]
	v_mfma_f32_16x16x32_bf16 v[18:21], v[168:171], v[212:215], v[18:21]
	s_setprio 0
	s_barrier
	s_add_u32 s20, s66, 0xb0080
	s_addc_u32 s21, s67, 0
	s_add_i32 s19, s22, s9
	v_lshl_add_u64 v[156:157], s[20:21], 0, v[144:145]
	s_mov_b32 m0, s19
	s_nop 0
	global_load_lds_dwordx4 v[156:157], off
	v_lshl_add_u64 v[156:157], s[20:21], 0, v[140:141]
	s_add_i32 m0, s19, 0x2000
	s_nop 0
	global_load_lds_dwordx4 v[156:157], off
	s_waitcnt vmcnt(6)
	s_barrier
	s_setprio 1
	v_mfma_f32_16x16x32_bf16 v[46:49], v[216:219], v[172:175], v[46:49]
	v_mfma_f32_16x16x32_bf16 v[42:45], v[224:227], v[172:175], v[42:45]
	v_mfma_f32_16x16x32_bf16 v[30:33], v[216:219], v[192:195], v[30:33]
	v_mfma_f32_16x16x32_bf16 v[26:29], v[224:227], v[192:195], v[26:29]
	v_mfma_f32_16x16x32_bf16 v[14:17], v[216:219], v[200:203], v[14:17]
	v_mfma_f32_16x16x32_bf16 v[10:13], v[224:227], v[200:203], v[10:13]
	v_mfma_f32_16x16x32_bf16 v[4:7], v[216:219], v[208:211], v[4:7]
	v_mfma_f32_16x16x32_bf16 v[0:3], v[224:227], v[208:211], v[0:3]
	v_mfma_f32_16x16x32_bf16 v[46:49], v[220:223], v[188:191], v[46:49]
	v_mfma_f32_16x16x32_bf16 v[42:45], v[228:231], v[188:191], v[42:45]
	v_mfma_f32_16x16x32_bf16 v[30:33], v[220:223], v[196:199], v[30:33]
	v_mfma_f32_16x16x32_bf16 v[26:29], v[228:231], v[196:199], v[26:29]
	v_mfma_f32_16x16x32_bf16 v[14:17], v[220:223], v[204:207], v[14:17]
	v_mfma_f32_16x16x32_bf16 v[10:13], v[228:231], v[204:207], v[10:13]
	v_mfma_f32_16x16x32_bf16 v[4:7], v[220:223], v[212:215], v[4:7]
	v_mfma_f32_16x16x32_bf16 v[0:3], v[228:231], v[212:215], v[0:3]
	s_setprio 0
	s_add_i32 s18, s18, 2
	s_add_u32 s16, s16, 0x100
	s_addc_u32 s17, s17, 0
	s_cmp_gt_u32 s18, 41
	s_mov_b64 s[42:43], s[72:73]
	s_barrier
	s_cbranch_scc0 .LBB0_825
	s_cmp_lg_u64 s[38:39], 0
	s_cbranch_scc1 .Lgdr818_e
	s_add_u32 s100, s40, 0x0
	s_addc_u32 s101, s41, 0
	v_lshl_add_u64 v[216:217], s[100:101], 0, v[148:149]
	s_add_i32 m0, s11, 0xc000
	s_nop 0
	global_load_lds_dwordx4 v[216:217], off
	v_lshl_add_u64 v[216:217], s[100:101], 0, v[150:151]
	s_add_i32 m0, s11, 0xe000
	s_nop 0
	global_load_lds_dwordx4 v[216:217], off
	s_mov_b32 s98, 1
; __device__ __forceinline__ unsigned pk_bf16(float a, float b) { f32x2 v = {a, b}; bf2_t r = __builtin_convertvector(v, bf2_t); return __builtin_bit_cast(unsigned, r); }
; #define PG8_WAIT_V(n) asm volatile("s_waitcnt vmcnt(" #n ")" ::: "memory")
; #define PG8_BAR __builtin_amdgcn_s_barrier()
;     __device__ __forceinline__ void operator()(const f32x4 (&acc)[2][2][4][2], const Unit& u, int wr, int wc, int fr, int fq) const {
;         const int row0 = u.pm * BM + wr * 64 + fr; int colt = u.pn * BM; bf16_t* base = O;
;         if (split_cols) { const int t = colt / split_cols; base += (size_t)t * split_stride; colt -= t * split_cols; }
;         const int col0 = colt + wc * 32 + 8 * fq;
; #pragma unroll
;         for (int ai = 0; ai < 2; ++ai)
; #pragma unroll
;             for (int m = 0; m < 4; ++m) { const int row = row0 + ai * HALF + m * 16;
;                 bf16_t* rowp = slot_stride ? base + (size_t)(colt >> 7) * slot_stride + (size_t)row * 128 + wc * 32 + 8 * fq : base + (size_t)row * ldc + col0;
; #pragma unroll
;                 for (int bj = 0; bj < 2; ++bj) { const f32x4 v0 = acc[ai][bj][m][0], v1 = acc[ai][bj][m][1];
;                     u32x4 w; w.x = pk_bf16(v0[0], v0[1]); w.y = pk_bf16(v0[2], v0[3]); w.z = pk_bf16(v1[0], v1[1]); w.w = pk_bf16(v1[2], v1[3]);
;                     *(u32x4*)(rowp + (slot_stride ? (size_t)bj * slot_stride : (size_t)bj * HALF)) = w; } }
; template <class Epi, class Sched>
; __device__ __forceinline__ void gemm_phase(LAS unsigned char* lds, const Gemm g, const Sched& S, const Epi& E) {
;     ...
;         E(acc, cur, wr, wc, fr, fq); S.done(cur);
;         if (!has_next) break;
; #pragma unroll
;         for (int a = 0; a < 2; ++a)
; #pragma unroll
;             for (int b = 0; b < 2; ++b)
; #pragma unroll
;                 for (int m = 0; m < 4; ++m)
; #pragma unroll
;                     for (int n = 0; n < 2; ++n) acc[a][b][m][n] = (f32x4){0.f, 0.f, 0.f, 0.f};
;         cur = nxt; cA = nA; cB = nB; ++ui;
;     }
;     PG8_WAIT_V(0);
;     if (wr == 0) PG8_BAR;
;     PG8_BAR;
.Lgdr818_e:
	v_lshl_add_u32 v156, s78, 8, v9
	v_lshl_or_b32 v158, s75, 8, v153
	v_readlane_b32 s16, v244, 38
	v_ashrrev_i32_e32 v159, 31, v158
	v_readlane_b32 s17, v244, 39
	v_ashrrev_i32_e32 v157, 31, v156
	v_lshlrev_b64 v[160:161], 11, v[156:157]
	v_lshl_add_u64 v[158:159], v[158:159], 1, s[16:17]
	v_lshl_add_u64 v[160:161], v[158:159], 0, v[160:161]
	s_mov_b64 s[16:17], 0x40000
	v_cvt_pk_bf16_f32 v70, v70, v71
	v_cvt_pk_bf16_f32 v71, v72, v73
	v_cvt_pk_bf16_f32 v72, v66, v67
	v_lshl_add_u64 v[66:67], v[160:161], 0, s[16:17]
	s_mov_b32 s16, 0x40000
	v_cvt_pk_bf16_f32 v62, v62, v63
	v_cvt_pk_bf16_f32 v63, v64, v65
	v_cvt_pk_bf16_f32 v64, v58, v59
	v_add_co_u32_e32 v58, vcc, s16, v160
	v_cvt_pk_bf16_f32 v46, v46, v47
	v_cvt_pk_bf16_f32 v47, v48, v49
	v_cvt_pk_bf16_f32 v48, v42, v43
	v_cvt_pk_bf16_f32 v49, v44, v45
	s_mov_b64 s[16:17], 0x48000
	v_addc_co_u32_e32 v59, vcc, 0, v161, vcc
	global_store_dwordx4 v[66:67], v[46:49], off offset:256
	v_cvt_pk_bf16_f32 v30, v30, v31
	v_cvt_pk_bf16_f32 v31, v32, v33
	v_lshl_add_u64 v[46:47], v[160:161], 0, s[16:17]
	s_mov_b32 s16, 0x48000
	v_add_co_u32_e32 v48, vcc, s16, v160
	v_cvt_pk_bf16_f32 v32, v26, v27
	v_cvt_pk_bf16_f32 v33, v28, v29
	s_mov_b64 s[16:17], 0x50000
	v_cvt_pk_bf16_f32 v110, v110, v111
	v_cvt_pk_bf16_f32 v111, v112, v113
	v_cvt_pk_bf16_f32 v112, v106, v107
	v_or_b32_e32 v106, 16, v156
	v_addc_co_u32_e32 v49, vcc, 0, v161, vcc
	global_store_dwordx4 v[46:47], v[30:33], off offset:256
	v_ashrrev_i32_e32 v107, 31, v106
	v_cvt_pk_bf16_f32 v94, v94, v95
	v_lshl_add_u64 v[30:31], v[160:161], 0, s[16:17]
	s_mov_b32 s16, 0x50000
	v_cvt_pk_bf16_f32 v95, v96, v97
	v_cvt_pk_bf16_f32 v96, v90, v91
	v_or_b32_e32 v90, 32, v156
	v_add_co_u32_e32 v32, vcc, s16, v160
	v_cvt_pk_bf16_f32 v14, v14, v15
	v_cvt_pk_bf16_f32 v15, v16, v17
	v_cvt_pk_bf16_f32 v16, v10, v11
	v_cvt_pk_bf16_f32 v17, v12, v13
	s_mov_b64 s[16:17], 0x58000
	v_cvt_pk_bf16_f32 v113, v108, v109
	v_lshlrev_b64 v[106:107], 11, v[106:107]
	v_ashrrev_i32_e32 v91, 31, v90
	v_cvt_pk_bf16_f32 v78, v78, v79
	v_cvt_pk_bf16_f32 v79, v80, v81
	v_cvt_pk_bf16_f32 v80, v74, v75
	v_or_b32_e32 v74, 48, v156
	v_addc_co_u32_e32 v33, vcc, 0, v161, vcc
	global_store_dwordx4 v[30:31], v[14:17], off offset:256
	global_store_dwordx4 v[160:161], v[110:113], off offset:256
	v_cvt_pk_bf16_f32 v97, v92, v93
	v_lshl_add_u64 v[14:15], v[160:161], 0, s[16:17]
	s_mov_b32 s16, 0x58000
	v_lshl_add_u64 v[110:111], v[158:159], 0, v[106:107]
	v_lshlrev_b64 v[90:91], 11, v[90:91]
	v_ashrrev_i32_e32 v75, 31, v74
	v_add_co_u32_e32 v16, vcc, s16, v160
	global_store_dwordx4 v[110:111], v[94:97], off offset:256
	v_cvt_pk_bf16_f32 v81, v76, v77
	v_lshlrev_b64 v[74:75], 11, v[74:75]
	v_lshl_add_u64 v[94:95], v[158:159], 0, v[90:91]
	v_addc_co_u32_e32 v17, vcc, 0, v161, vcc
	v_readlane_b32 s70, v244, 55
	v_cvt_pk_bf16_f32 v126, v126, v127
	v_cvt_pk_bf16_f32 v127, v128, v129
	v_cvt_pk_bf16_f32 v128, v122, v123
	v_cvt_pk_bf16_f32 v129, v124, v125
	v_cvt_pk_bf16_f32 v106, v118, v119
	v_cvt_pk_bf16_f32 v107, v120, v121
	v_cvt_pk_bf16_f32 v108, v114, v115
	v_cvt_pk_bf16_f32 v109, v116, v117
	v_cvt_pk_bf16_f32 v90, v102, v103
	v_cvt_pk_bf16_f32 v91, v104, v105
	v_cvt_pk_bf16_f32 v92, v98, v99
	v_cvt_pk_bf16_f32 v93, v100, v101
	global_store_dwordx4 v[94:95], v[78:81], off offset:256
	v_cvt_pk_bf16_f32 v76, v82, v83
	v_cvt_pk_bf16_f32 v77, v84, v85
	v_lshl_add_u64 v[78:79], v[158:159], 0, v[74:75]
	v_cvt_pk_bf16_f32 v74, v86, v87
	v_cvt_pk_bf16_f32 v75, v88, v89
	v_cvt_pk_bf16_f32 v73, v68, v69
	v_cvt_pk_bf16_f32 v65, v60, v61
	v_cvt_pk_bf16_f32 v42, v54, v55
	v_cvt_pk_bf16_f32 v43, v56, v57
	v_cvt_pk_bf16_f32 v44, v50, v51
	v_cvt_pk_bf16_f32 v45, v52, v53
	v_cvt_pk_bf16_f32 v26, v38, v39
	v_cvt_pk_bf16_f32 v27, v40, v41
	v_cvt_pk_bf16_f32 v28, v34, v35
	v_cvt_pk_bf16_f32 v29, v36, v37
	v_cvt_pk_bf16_f32 v10, v22, v23
	v_cvt_pk_bf16_f32 v11, v24, v25
	v_cvt_pk_bf16_f32 v12, v18, v19
	v_cvt_pk_bf16_f32 v13, v20, v21
	v_cvt_pk_bf16_f32 v4, v4, v5
	v_cvt_pk_bf16_f32 v5, v6, v7
	v_cvt_pk_bf16_f32 v6, v0, v1
	v_cvt_pk_bf16_f32 v7, v2, v3
	s_and_b64 vcc, exec, s[38:39]
	s_mov_b32 s75, s85
	s_mov_b32 s78, s88
	s_mov_b64 s[72:73], s[0:1]
	s_mov_b64 s[42:43], s[40:41]
	v_readlane_b32 s71, v244, 56
	global_store_dwordx4 v[160:161], v[126:129], off
	global_store_dwordx4 v[110:111], v[106:109], off
	global_store_dwordx4 v[94:95], v[90:93], off
	global_store_dwordx4 v[78:79], v[74:77], off
	global_store_dwordx4 v[78:79], v[70:73], off offset:256
	global_store_dwordx4 v[58:59], v[62:65], off
	global_store_dwordx4 v[48:49], v[42:45], off
	global_store_dwordx4 v[32:33], v[26:29], off
	global_store_dwordx4 v[16:17], v[10:13], off
	global_store_dwordx4 v[14:15], v[4:7], off offset:256
	s_cbranch_vccz .LBB0_818
	s_waitcnt vmcnt(0)
	v_readlane_b32 s16, v244, 51
	s_cmpk_gt_u32 s6, 0xff
	v_readlane_b32 s17, v244, 52
	s_cbranch_scc1 .LBB0_829
	s_barrier
